# deferred DN transposition with nt (streaming) loads/stores in the transposer
# baseline (speedup 1.0000x reference)
; __device__ __forceinline__ unsigned cvt_pk_bf16(float lo, float hi) { unsigned r; asm volatile("v_cvt_pk_bf16_f32 %0, %1, %2" : "=v"(r) : "v"(lo), "v"(hi)); return r; }
; #define GAS __attribute__((address_space(1)))
; #define LAS __attribute__((address_space(3)))
; #define LDS_WAIT() asm volatile("s_waitcnt lgkmcnt(0)" ::: "memory")
;     const int nblk = N / 32, kb = item / nblk, nb = item % nblk, k0 = 128 * kb, n0 = 32 * nb;
;     const int nd0 = GLU ? (n0 < 6144 ? 256 * (n0 >> 7) + (n0 & 127) : 256 * ((n0 - 6144) >> 7) + 128 + ((n0 - 6144) & 127)) : n0;
; #pragma unroll 32
;     for (int i = 0; i < 64; ++i) { const int kk = 2 * i + (lane >> 5); scr[kk * 33 + (lane & 31)] = W[(size_t)(k0 + kk) * N + n0 + (lane & 31)]; }
;     LDS_WAIT(); asm volatile("" ::: "memory");
;     const int c = lane & 15;
;     float gk[8];
;     if (gain) load8f(gain + k0 + 8 * c, gk); else {
; #pragma unroll
;         for (int e = 0; e < 8; ++e) gk[e] = 1.0f; }
; #pragma unroll
;     for (int j = 0; j < 8; ++j) { const int n = (lane >> 4) + 4 * j; const LAS float* s = scr + (8 * c) * 33 + n;
;         v4u o; o.x = cvt_pk_bf16(s[0 * 33] * gk[0], s[1 * 33] * gk[1]); o.y = cvt_pk_bf16(s[2 * 33] * gk[2], s[3 * 33] * gk[3]); o.z = cvt_pk_bf16(s[4 * 33] * gk[4], s[5 * 33] * gk[5]); o.w = cvt_pk_bf16(s[6 * 33] * gk[6], s[7 * 33] * gk[7]);
;         *(GAS v4u*)(WT + (size_t)(nd0 + n) * K + k0 + 8 * c) = o; }
.LBB0_1082:
	s_cmp_lg_u32 s83, 0x100
	s_cbranch_scc1 .Ldfr_skip
	s_cmp_lt_u32 s79, 0x80
	s_cbranch_scc1 .Ldfr_skip
	s_mov_b64 s[34:35], exec
	s_mov_b64 exec, -1
	s_load_dwordx2 s[0:1], s[86:87], 0xd8
	s_load_dwordx2 s[2:3], s[86:87], 0xe8
	v_mbcnt_lo_u32_b32 v0, -1, 0
	v_mbcnt_hi_u32_b32 v0, -1, v0
	s_sub_u32 s10, s79, 0x80
	s_lshl_b32 s10, s10, 3
	s_add_u32 s10, s10, s82
	s_mul_i32 s11, s82, 0x4400
	v_readlane_b32 s13, v255, 24
	v_lshrrev_b32_e32 v2, 3, v0
	v_and_b32_e32 v3, 7, v0
	v_lshlrev_b32_e32 v20, 13, v2
	v_lshl_add_u32 v20, v3, 4, v20
	v_add_u32_e32 v21, 0x10000, v20
	v_add_u32_e32 v22, 0x20000, v20
	v_add_u32_e32 v23, 0x30000, v20
	v_add_u32_e32 v24, 0x40000, v20
	v_add_u32_e32 v25, 0x50000, v20
	v_add_u32_e32 v26, 0x60000, v20
	v_add_u32_e32 v27, 0x70000, v20
	v_add_u32_e32 v28, 0x80000, v20
	v_add_u32_e32 v29, 0x90000, v20
	v_add_u32_e32 v30, 0xa0000, v20
	v_add_u32_e32 v31, 0xb0000, v20
	v_add_u32_e32 v32, 0xc0000, v20
	v_add_u32_e32 v33, 0xd0000, v20
	v_add_u32_e32 v34, 0xe0000, v20
	v_add_u32_e32 v35, 0xf0000, v20
	v_mul_u32_u24_e32 v36, 0x84, v2
	v_lshl_add_u32 v36, v3, 4, v36
	v_add_u32_e32 v36, s11, v36
	v_and_b32_e32 v2, 15, v0
	v_lshrrev_b32_e32 v3, 4, v0
	v_mul_u32_u24_e32 v52, 0x420, v2
	v_lshl_add_u32 v52, v3, 2, v52
	v_add_u32_e32 v52, s11, v52
	v_add_u32_e32 v53, 16, v52
	v_add_u32_e32 v54, 32, v52
	v_add_u32_e32 v55, 48, v52
	v_add_u32_e32 v56, 64, v52
	v_add_u32_e32 v57, 80, v52
	v_add_u32_e32 v58, 96, v52
	v_add_u32_e32 v59, 112, v52
	v_mul_u32_u24_e32 v60, 0x3000, v3
	v_lshl_add_u32 v60, v2, 4, v60
	v_add_u32_e32 v61, 0xc000, v60
	v_add_u32_e32 v62, 0x18000, v60
	v_add_u32_e32 v63, 0x24000, v60
	v_add_u32_e32 v64, 0x30000, v60
	v_add_u32_e32 v65, 0x3c000, v60
	v_add_u32_e32 v66, 0x48000, v60
	v_add_u32_e32 v67, 0x54000, v60
	s_waitcnt lgkmcnt(0)
	s_add_u32 s2, s2, 0x14600000
	s_addc_u32 s3, s3, 0
	s_cmp_lg_u32 s13, 0
	s_cbranch_scc1 .Ldfr_p1
	s_mov_b32 s16, s10
	s_lshr_b32 s20, s16, 6
	s_and_b32 s24, s16, 63
	s_lshl_b32 s20, s20, 20
	s_lshl_b32 s24, s24, 7
	s_add_i32 s20, s20, s24
	s_add_i32 s20, s20, 0x6000000
	s_add_u32 s26, s0, s20
	s_addc_u32 s27, s1, 0
	global_load_dwordx4 v[78:81], v20, s[26:27] nt
	global_load_dwordx4 v[82:85], v21, s[26:27] nt
	global_load_dwordx4 v[86:89], v22, s[26:27] nt
	global_load_dwordx4 v[90:93], v23, s[26:27] nt
	global_load_dwordx4 v[94:97], v24, s[26:27] nt
	global_load_dwordx4 v[98:101], v25, s[26:27] nt
	global_load_dwordx4 v[102:105], v26, s[26:27] nt
	global_load_dwordx4 v[106:109], v27, s[26:27] nt
	global_load_dwordx4 v[110:113], v28, s[26:27] nt
	global_load_dwordx4 v[114:117], v29, s[26:27] nt
	global_load_dwordx4 v[118:121], v30, s[26:27] nt
	global_load_dwordx4 v[122:125], v31, s[26:27] nt
	global_load_dwordx4 v[126:129], v32, s[26:27] nt
	global_load_dwordx4 v[130:133], v33, s[26:27] nt
	global_load_dwordx4 v[134:137], v34, s[26:27] nt
	global_load_dwordx4 v[138:141], v35, s[26:27] nt
	s_add_i32 s16, s10, 0x400
	s_lshr_b32 s20, s16, 6
	s_and_b32 s24, s16, 63
	s_lshl_b32 s20, s20, 20
	s_lshl_b32 s24, s24, 7
	s_add_i32 s20, s20, s24
	s_add_i32 s20, s20, 0x6000000
	s_add_u32 s26, s0, s20
	s_addc_u32 s27, s1, 0
	global_load_dwordx4 v[142:145], v20, s[26:27] nt
	global_load_dwordx4 v[146:149], v21, s[26:27] nt
	global_load_dwordx4 v[150:153], v22, s[26:27] nt
	global_load_dwordx4 v[154:157], v23, s[26:27] nt
	global_load_dwordx4 v[158:161], v24, s[26:27] nt
	global_load_dwordx4 v[162:165], v25, s[26:27] nt
	global_load_dwordx4 v[196:199], v26, s[26:27] nt
	global_load_dwordx4 v[200:203], v27, s[26:27] nt
	global_load_dwordx4 v[204:207], v28, s[26:27] nt
	global_load_dwordx4 v[208:211], v29, s[26:27] nt
	global_load_dwordx4 v[212:215], v30, s[26:27] nt
	global_load_dwordx4 v[216:219], v31, s[26:27] nt
	global_load_dwordx4 v[228:231], v32, s[26:27] nt
	global_load_dwordx4 v[232:235], v33, s[26:27] nt
	global_load_dwordx4 v[236:239], v34, s[26:27] nt
	global_load_dwordx4 v[240:243], v35, s[26:27] nt
	s_mov_b32 s16, s10
	s_lshr_b32 s20, s16, 6
	s_and_b32 s24, s16, 63
	s_mul_i32 s24, s24, 0x60000
	s_lshl_b32 s20, s20, 8
	s_add_i32 s20, s20, s24
	s_add_i32 s20, s20, 0x3000000
	s_add_u32 s28, s2, s20
	s_addc_u32 s29, s3, 0
	s_waitcnt vmcnt(31)
	ds_write2_b32 v36, v78, v79 offset1:1
	ds_write2_b32 v36, v80, v81 offset0:2 offset1:3
	s_waitcnt vmcnt(30)
	v_add_u32_e32 v49, 0x420, v36
	ds_write2_b32 v49, v82, v83 offset1:1
	ds_write2_b32 v49, v84, v85 offset0:2 offset1:3
	s_waitcnt vmcnt(29)
	v_add_u32_e32 v48, 0x840, v36
	ds_write2_b32 v48, v86, v87 offset1:1
	ds_write2_b32 v48, v88, v89 offset0:2 offset1:3
	s_waitcnt vmcnt(28)
	v_add_u32_e32 v49, 0xc60, v36
	ds_write2_b32 v49, v90, v91 offset1:1
	ds_write2_b32 v49, v92, v93 offset0:2 offset1:3
	s_waitcnt vmcnt(27)
	v_add_u32_e32 v48, 0x1080, v36
	ds_write2_b32 v48, v94, v95 offset1:1
	ds_write2_b32 v48, v96, v97 offset0:2 offset1:3
	s_waitcnt vmcnt(26)
	v_add_u32_e32 v49, 0x14a0, v36
	ds_write2_b32 v49, v98, v99 offset1:1
	ds_write2_b32 v49, v100, v101 offset0:2 offset1:3
	s_waitcnt vmcnt(25)
	v_add_u32_e32 v48, 0x18c0, v36
	ds_write2_b32 v48, v102, v103 offset1:1
	ds_write2_b32 v48, v104, v105 offset0:2 offset1:3
	s_waitcnt vmcnt(24)
	v_add_u32_e32 v49, 0x1ce0, v36
	ds_write2_b32 v49, v106, v107 offset1:1
	ds_write2_b32 v49, v108, v109 offset0:2 offset1:3
	s_waitcnt vmcnt(23)
	v_add_u32_e32 v48, 0x2100, v36
	ds_write2_b32 v48, v110, v111 offset1:1
	ds_write2_b32 v48, v112, v113 offset0:2 offset1:3
	s_waitcnt vmcnt(22)
	v_add_u32_e32 v49, 0x2520, v36
	ds_write2_b32 v49, v114, v115 offset1:1
	ds_write2_b32 v49, v116, v117 offset0:2 offset1:3
	s_waitcnt vmcnt(21)
; __device__ __forceinline__ unsigned cvt_pk_bf16(float lo, float hi) { unsigned r; asm volatile("v_cvt_pk_bf16_f32 %0, %1, %2" : "=v"(r) : "v"(lo), "v"(hi)); return r; }
; #define GAS __attribute__((address_space(1)))
; #define LAS __attribute__((address_space(3)))
; #define LDS_WAIT() asm volatile("s_waitcnt lgkmcnt(0)" ::: "memory")
;     ...
;     for (int i = 0; i < 64; ++i) { const int kk = 2 * i + (lane >> 5); scr[kk * 33 + (lane & 31)] = W[(size_t)(k0 + kk) * N + n0 + (lane & 31)]; }
;     LDS_WAIT(); asm volatile("" ::: "memory");
;     const int c = lane & 15;
;     float gk[8];
;     if (gain) load8f(gain + k0 + 8 * c, gk); else {
; #pragma unroll
;         for (int e = 0; e < 8; ++e) gk[e] = 1.0f; }
; #pragma unroll
;     for (int j = 0; j < 8; ++j) { const int n = (lane >> 4) + 4 * j; const LAS float* s = scr + (8 * c) * 33 + n;
;         v4u o; o.x = cvt_pk_bf16(s[0 * 33] * gk[0], s[1 * 33] * gk[1]); o.y = cvt_pk_bf16(s[2 * 33] * gk[2], s[3 * 33] * gk[3]); o.z = cvt_pk_bf16(s[4 * 33] * gk[4], s[5 * 33] * gk[5]); o.w = cvt_pk_bf16(s[6 * 33] * gk[6], s[7 * 33] * gk[7]);
;         *(GAS v4u*)(WT + (size_t)(nd0 + n) * K + k0 + 8 * c) = o; }
	v_add_u32_e32 v48, 0x2940, v36
	ds_write2_b32 v48, v118, v119 offset1:1
	ds_write2_b32 v48, v120, v121 offset0:2 offset1:3
	s_waitcnt vmcnt(20)
	v_add_u32_e32 v49, 0x2d60, v36
	ds_write2_b32 v49, v122, v123 offset1:1
	ds_write2_b32 v49, v124, v125 offset0:2 offset1:3
	s_waitcnt vmcnt(19)
	v_add_u32_e32 v48, 0x3180, v36
	ds_write2_b32 v48, v126, v127 offset1:1
	ds_write2_b32 v48, v128, v129 offset0:2 offset1:3
	s_waitcnt vmcnt(18)
	v_add_u32_e32 v49, 0x35a0, v36
	ds_write2_b32 v49, v130, v131 offset1:1
	ds_write2_b32 v49, v132, v133 offset0:2 offset1:3
	s_waitcnt vmcnt(17)
	v_add_u32_e32 v48, 0x39c0, v36
	ds_write2_b32 v48, v134, v135 offset1:1
	ds_write2_b32 v48, v136, v137 offset0:2 offset1:3
	s_waitcnt vmcnt(16)
	v_add_u32_e32 v49, 0x3de0, v36
	ds_write2_b32 v49, v138, v139 offset1:1
	ds_write2_b32 v49, v140, v141 offset0:2 offset1:3
	ds_read2_b32 v[244:245], v52 offset0:0 offset1:33
	ds_read2_b32 v[246:247], v52 offset0:66 offset1:99
	ds_read2_b32 v[248:249], v52 offset0:132 offset1:165
	ds_read2_b32 v[250:251], v52 offset0:198 offset1:231
	ds_read2_b32 v[38:39], v53 offset0:0 offset1:33
	ds_read2_b32 v[40:41], v53 offset0:66 offset1:99
	ds_read2_b32 v[42:43], v53 offset0:132 offset1:165
	ds_read2_b32 v[44:45], v53 offset0:198 offset1:231
	s_waitcnt lgkmcnt(4)
	v_cvt_pk_bf16_f32 v170, v244, v245
	v_cvt_pk_bf16_f32 v171, v246, v247
	v_cvt_pk_bf16_f32 v172, v248, v249
	v_cvt_pk_bf16_f32 v173, v250, v251
	global_store_dwordx4 v60, v[170:173], s[28:29] nt
	ds_read2_b32 v[244:245], v54 offset0:0 offset1:33
	ds_read2_b32 v[246:247], v54 offset0:66 offset1:99
	ds_read2_b32 v[248:249], v54 offset0:132 offset1:165
	ds_read2_b32 v[250:251], v54 offset0:198 offset1:231
	s_waitcnt lgkmcnt(4)
	v_cvt_pk_bf16_f32 v176, v38, v39
	v_cvt_pk_bf16_f32 v177, v40, v41
	v_cvt_pk_bf16_f32 v178, v42, v43
	v_cvt_pk_bf16_f32 v179, v44, v45
	global_store_dwordx4 v61, v[176:179], s[28:29] nt
	ds_read2_b32 v[38:39], v55 offset0:0 offset1:33
	ds_read2_b32 v[40:41], v55 offset0:66 offset1:99
	ds_read2_b32 v[42:43], v55 offset0:132 offset1:165
	ds_read2_b32 v[44:45], v55 offset0:198 offset1:231
	s_waitcnt lgkmcnt(4)
	v_cvt_pk_bf16_f32 v170, v244, v245
	v_cvt_pk_bf16_f32 v171, v246, v247
	v_cvt_pk_bf16_f32 v172, v248, v249
	v_cvt_pk_bf16_f32 v173, v250, v251
	global_store_dwordx4 v62, v[170:173], s[28:29] nt
	ds_read2_b32 v[244:245], v56 offset0:0 offset1:33
	ds_read2_b32 v[246:247], v56 offset0:66 offset1:99
	ds_read2_b32 v[248:249], v56 offset0:132 offset1:165
	ds_read2_b32 v[250:251], v56 offset0:198 offset1:231
	s_waitcnt lgkmcnt(4)
	v_cvt_pk_bf16_f32 v176, v38, v39
	v_cvt_pk_bf16_f32 v177, v40, v41
	v_cvt_pk_bf16_f32 v178, v42, v43
	v_cvt_pk_bf16_f32 v179, v44, v45
	global_store_dwordx4 v63, v[176:179], s[28:29] nt
	ds_read2_b32 v[38:39], v57 offset0:0 offset1:33
	ds_read2_b32 v[40:41], v57 offset0:66 offset1:99
	ds_read2_b32 v[42:43], v57 offset0:132 offset1:165
	ds_read2_b32 v[44:45], v57 offset0:198 offset1:231
	s_waitcnt lgkmcnt(4)
	v_cvt_pk_bf16_f32 v170, v244, v245
	v_cvt_pk_bf16_f32 v171, v246, v247
	v_cvt_pk_bf16_f32 v172, v248, v249
	v_cvt_pk_bf16_f32 v173, v250, v251
	global_store_dwordx4 v64, v[170:173], s[28:29] nt
	ds_read2_b32 v[244:245], v58 offset0:0 offset1:33
	ds_read2_b32 v[246:247], v58 offset0:66 offset1:99
	ds_read2_b32 v[248:249], v58 offset0:132 offset1:165
	ds_read2_b32 v[250:251], v58 offset0:198 offset1:231
	s_waitcnt lgkmcnt(4)
	v_cvt_pk_bf16_f32 v176, v38, v39
	v_cvt_pk_bf16_f32 v177, v40, v41
	v_cvt_pk_bf16_f32 v178, v42, v43
	v_cvt_pk_bf16_f32 v179, v44, v45
	global_store_dwordx4 v65, v[176:179], s[28:29] nt
	ds_read2_b32 v[38:39], v59 offset0:0 offset1:33
	ds_read2_b32 v[40:41], v59 offset0:66 offset1:99
	ds_read2_b32 v[42:43], v59 offset0:132 offset1:165
	ds_read2_b32 v[44:45], v59 offset0:198 offset1:231
	s_waitcnt lgkmcnt(4)
	v_cvt_pk_bf16_f32 v170, v244, v245
	v_cvt_pk_bf16_f32 v171, v246, v247
	v_cvt_pk_bf16_f32 v172, v248, v249
	v_cvt_pk_bf16_f32 v173, v250, v251
	global_store_dwordx4 v66, v[170:173], s[28:29] nt
	s_waitcnt lgkmcnt(0)
	v_cvt_pk_bf16_f32 v176, v38, v39
	v_cvt_pk_bf16_f32 v177, v40, v41
	v_cvt_pk_bf16_f32 v178, v42, v43
	v_cvt_pk_bf16_f32 v179, v44, v45
	global_store_dwordx4 v67, v[176:179], s[28:29] nt
	s_add_i32 s16, s10, 0x800
	s_lshr_b32 s20, s16, 6
	s_and_b32 s24, s16, 63
	s_lshl_b32 s20, s20, 20
	s_lshl_b32 s24, s24, 7
	s_add_i32 s20, s20, s24
	s_add_i32 s20, s20, 0x6000000
	s_add_u32 s26, s0, s20
	s_addc_u32 s27, s1, 0
	global_load_dwordx4 v[78:81], v20, s[26:27] nt
	global_load_dwordx4 v[82:85], v21, s[26:27] nt
	global_load_dwordx4 v[86:89], v22, s[26:27] nt
	global_load_dwordx4 v[90:93], v23, s[26:27] nt
	global_load_dwordx4 v[94:97], v24, s[26:27] nt
	global_load_dwordx4 v[98:101], v25, s[26:27] nt
	global_load_dwordx4 v[102:105], v26, s[26:27] nt
	global_load_dwordx4 v[106:109], v27, s[26:27] nt
	global_load_dwordx4 v[110:113], v28, s[26:27] nt
	global_load_dwordx4 v[114:117], v29, s[26:27] nt
	global_load_dwordx4 v[118:121], v30, s[26:27] nt
	global_load_dwordx4 v[122:125], v31, s[26:27] nt
	global_load_dwordx4 v[126:129], v32, s[26:27] nt
	global_load_dwordx4 v[130:133], v33, s[26:27] nt
	global_load_dwordx4 v[134:137], v34, s[26:27] nt
	global_load_dwordx4 v[138:141], v35, s[26:27] nt
	s_add_i32 s16, s10, 0x400
	s_lshr_b32 s20, s16, 6
	s_and_b32 s24, s16, 63
	s_mul_i32 s24, s24, 0x60000
	s_lshl_b32 s20, s20, 8
	s_add_i32 s20, s20, s24
	s_add_i32 s20, s20, 0x3000000
	s_add_u32 s28, s2, s20
	s_addc_u32 s29, s3, 0
	s_waitcnt vmcnt(39)
	ds_write2_b32 v36, v142, v143 offset1:1
	ds_write2_b32 v36, v144, v145 offset0:2 offset1:3
	s_waitcnt vmcnt(38)
; __device__ __forceinline__ unsigned cvt_pk_bf16(float lo, float hi) { unsigned r; asm volatile("v_cvt_pk_bf16_f32 %0, %1, %2" : "=v"(r) : "v"(lo), "v"(hi)); return r; }
; #define GAS __attribute__((address_space(1)))
; #define LAS __attribute__((address_space(3)))
; #define LDS_WAIT() asm volatile("s_waitcnt lgkmcnt(0)" ::: "memory")
;     ...
;     for (int i = 0; i < 64; ++i) { const int kk = 2 * i + (lane >> 5); scr[kk * 33 + (lane & 31)] = W[(size_t)(k0 + kk) * N + n0 + (lane & 31)]; }
;     LDS_WAIT(); asm volatile("" ::: "memory");
;     const int c = lane & 15;
;     float gk[8];
;     if (gain) load8f(gain + k0 + 8 * c, gk); else {
; #pragma unroll
;         for (int e = 0; e < 8; ++e) gk[e] = 1.0f; }
; #pragma unroll
;     for (int j = 0; j < 8; ++j) { const int n = (lane >> 4) + 4 * j; const LAS float* s = scr + (8 * c) * 33 + n;
;         v4u o; o.x = cvt_pk_bf16(s[0 * 33] * gk[0], s[1 * 33] * gk[1]); o.y = cvt_pk_bf16(s[2 * 33] * gk[2], s[3 * 33] * gk[3]); o.z = cvt_pk_bf16(s[4 * 33] * gk[4], s[5 * 33] * gk[5]); o.w = cvt_pk_bf16(s[6 * 33] * gk[6], s[7 * 33] * gk[7]);
;         *(GAS v4u*)(WT + (size_t)(nd0 + n) * K + k0 + 8 * c) = o; }
	v_add_u32_e32 v49, 0x420, v36
	ds_write2_b32 v49, v146, v147 offset1:1
	ds_write2_b32 v49, v148, v149 offset0:2 offset1:3
	s_waitcnt vmcnt(37)
	v_add_u32_e32 v48, 0x840, v36
	ds_write2_b32 v48, v150, v151 offset1:1
	ds_write2_b32 v48, v152, v153 offset0:2 offset1:3
	s_waitcnt vmcnt(36)
	v_add_u32_e32 v49, 0xc60, v36
	ds_write2_b32 v49, v154, v155 offset1:1
	ds_write2_b32 v49, v156, v157 offset0:2 offset1:3
	s_waitcnt vmcnt(35)
	v_add_u32_e32 v48, 0x1080, v36
	ds_write2_b32 v48, v158, v159 offset1:1
	ds_write2_b32 v48, v160, v161 offset0:2 offset1:3
	s_waitcnt vmcnt(34)
	v_add_u32_e32 v49, 0x14a0, v36
	ds_write2_b32 v49, v162, v163 offset1:1
	ds_write2_b32 v49, v164, v165 offset0:2 offset1:3
	s_waitcnt vmcnt(33)
	v_add_u32_e32 v48, 0x18c0, v36
	ds_write2_b32 v48, v196, v197 offset1:1
	ds_write2_b32 v48, v198, v199 offset0:2 offset1:3
	s_waitcnt vmcnt(32)
	v_add_u32_e32 v49, 0x1ce0, v36
	ds_write2_b32 v49, v200, v201 offset1:1
	ds_write2_b32 v49, v202, v203 offset0:2 offset1:3
	s_waitcnt vmcnt(31)
	v_add_u32_e32 v48, 0x2100, v36
	ds_write2_b32 v48, v204, v205 offset1:1
	ds_write2_b32 v48, v206, v207 offset0:2 offset1:3
	s_waitcnt vmcnt(30)
	v_add_u32_e32 v49, 0x2520, v36
	ds_write2_b32 v49, v208, v209 offset1:1
	ds_write2_b32 v49, v210, v211 offset0:2 offset1:3
	s_waitcnt vmcnt(29)
	v_add_u32_e32 v48, 0x2940, v36
	ds_write2_b32 v48, v212, v213 offset1:1
	ds_write2_b32 v48, v214, v215 offset0:2 offset1:3
	s_waitcnt vmcnt(28)
	v_add_u32_e32 v49, 0x2d60, v36
	ds_write2_b32 v49, v216, v217 offset1:1
	ds_write2_b32 v49, v218, v219 offset0:2 offset1:3
	s_waitcnt vmcnt(27)
	v_add_u32_e32 v48, 0x3180, v36
	ds_write2_b32 v48, v228, v229 offset1:1
	ds_write2_b32 v48, v230, v231 offset0:2 offset1:3
	s_waitcnt vmcnt(26)
	v_add_u32_e32 v49, 0x35a0, v36
	ds_write2_b32 v49, v232, v233 offset1:1
	ds_write2_b32 v49, v234, v235 offset0:2 offset1:3
	s_waitcnt vmcnt(25)
	v_add_u32_e32 v48, 0x39c0, v36
	ds_write2_b32 v48, v236, v237 offset1:1
	ds_write2_b32 v48, v238, v239 offset0:2 offset1:3
	s_waitcnt vmcnt(24)
	v_add_u32_e32 v49, 0x3de0, v36
	ds_write2_b32 v49, v240, v241 offset1:1
	ds_write2_b32 v49, v242, v243 offset0:2 offset1:3
	ds_read2_b32 v[244:245], v52 offset0:0 offset1:33
	ds_read2_b32 v[246:247], v52 offset0:66 offset1:99
	ds_read2_b32 v[248:249], v52 offset0:132 offset1:165
	ds_read2_b32 v[250:251], v52 offset0:198 offset1:231
	ds_read2_b32 v[38:39], v53 offset0:0 offset1:33
	ds_read2_b32 v[40:41], v53 offset0:66 offset1:99
	ds_read2_b32 v[42:43], v53 offset0:132 offset1:165
	ds_read2_b32 v[44:45], v53 offset0:198 offset1:231
	s_waitcnt lgkmcnt(4)
	v_cvt_pk_bf16_f32 v170, v244, v245
	v_cvt_pk_bf16_f32 v171, v246, v247
	v_cvt_pk_bf16_f32 v172, v248, v249
	v_cvt_pk_bf16_f32 v173, v250, v251
	global_store_dwordx4 v60, v[170:173], s[28:29] nt
	ds_read2_b32 v[244:245], v54 offset0:0 offset1:33
	ds_read2_b32 v[246:247], v54 offset0:66 offset1:99
	ds_read2_b32 v[248:249], v54 offset0:132 offset1:165
	ds_read2_b32 v[250:251], v54 offset0:198 offset1:231
	s_waitcnt lgkmcnt(4)
	v_cvt_pk_bf16_f32 v176, v38, v39
	v_cvt_pk_bf16_f32 v177, v40, v41
	v_cvt_pk_bf16_f32 v178, v42, v43
	v_cvt_pk_bf16_f32 v179, v44, v45
	global_store_dwordx4 v61, v[176:179], s[28:29] nt
	ds_read2_b32 v[38:39], v55 offset0:0 offset1:33
	ds_read2_b32 v[40:41], v55 offset0:66 offset1:99
	ds_read2_b32 v[42:43], v55 offset0:132 offset1:165
	ds_read2_b32 v[44:45], v55 offset0:198 offset1:231
	s_waitcnt lgkmcnt(4)
	v_cvt_pk_bf16_f32 v170, v244, v245
	v_cvt_pk_bf16_f32 v171, v246, v247
	v_cvt_pk_bf16_f32 v172, v248, v249
	v_cvt_pk_bf16_f32 v173, v250, v251
	global_store_dwordx4 v62, v[170:173], s[28:29] nt
	ds_read2_b32 v[244:245], v56 offset0:0 offset1:33
	ds_read2_b32 v[246:247], v56 offset0:66 offset1:99
	ds_read2_b32 v[248:249], v56 offset0:132 offset1:165
	ds_read2_b32 v[250:251], v56 offset0:198 offset1:231
	s_waitcnt lgkmcnt(4)
	v_cvt_pk_bf16_f32 v176, v38, v39
	v_cvt_pk_bf16_f32 v177, v40, v41
	v_cvt_pk_bf16_f32 v178, v42, v43
	v_cvt_pk_bf16_f32 v179, v44, v45
	global_store_dwordx4 v63, v[176:179], s[28:29] nt
	ds_read2_b32 v[38:39], v57 offset0:0 offset1:33
	ds_read2_b32 v[40:41], v57 offset0:66 offset1:99
	ds_read2_b32 v[42:43], v57 offset0:132 offset1:165
	ds_read2_b32 v[44:45], v57 offset0:198 offset1:231
	s_waitcnt lgkmcnt(4)
	v_cvt_pk_bf16_f32 v170, v244, v245
	v_cvt_pk_bf16_f32 v171, v246, v247
	v_cvt_pk_bf16_f32 v172, v248, v249
	v_cvt_pk_bf16_f32 v173, v250, v251
	global_store_dwordx4 v64, v[170:173], s[28:29] nt
	ds_read2_b32 v[244:245], v58 offset0:0 offset1:33
	ds_read2_b32 v[246:247], v58 offset0:66 offset1:99
	ds_read2_b32 v[248:249], v58 offset0:132 offset1:165
	ds_read2_b32 v[250:251], v58 offset0:198 offset1:231
	s_waitcnt lgkmcnt(4)
	v_cvt_pk_bf16_f32 v176, v38, v39
	v_cvt_pk_bf16_f32 v177, v40, v41
	v_cvt_pk_bf16_f32 v178, v42, v43
	v_cvt_pk_bf16_f32 v179, v44, v45
	global_store_dwordx4 v65, v[176:179], s[28:29] nt
	ds_read2_b32 v[38:39], v59 offset0:0 offset1:33
	ds_read2_b32 v[40:41], v59 offset0:66 offset1:99
	ds_read2_b32 v[42:43], v59 offset0:132 offset1:165
	ds_read2_b32 v[44:45], v59 offset0:198 offset1:231
	s_waitcnt lgkmcnt(4)
	v_cvt_pk_bf16_f32 v170, v244, v245
	v_cvt_pk_bf16_f32 v171, v246, v247
	v_cvt_pk_bf16_f32 v172, v248, v249
	v_cvt_pk_bf16_f32 v173, v250, v251
	global_store_dwordx4 v66, v[170:173], s[28:29] nt
	s_waitcnt lgkmcnt(0)
; __device__ __forceinline__ unsigned cvt_pk_bf16(float lo, float hi) { unsigned r; asm volatile("v_cvt_pk_bf16_f32 %0, %1, %2" : "=v"(r) : "v"(lo), "v"(hi)); return r; }
; #define GAS __attribute__((address_space(1)))
; #define LAS __attribute__((address_space(3)))
; #define LDS_WAIT() asm volatile("s_waitcnt lgkmcnt(0)" ::: "memory")
;     ...
;     for (int i = 0; i < 64; ++i) { const int kk = 2 * i + (lane >> 5); scr[kk * 33 + (lane & 31)] = W[(size_t)(k0 + kk) * N + n0 + (lane & 31)]; }
;     LDS_WAIT(); asm volatile("" ::: "memory");
;     const int c = lane & 15;
;     float gk[8];
;     if (gain) load8f(gain + k0 + 8 * c, gk); else {
; #pragma unroll
;         for (int e = 0; e < 8; ++e) gk[e] = 1.0f; }
; #pragma unroll
;     for (int j = 0; j < 8; ++j) { const int n = (lane >> 4) + 4 * j; const LAS float* s = scr + (8 * c) * 33 + n;
;         v4u o; o.x = cvt_pk_bf16(s[0 * 33] * gk[0], s[1 * 33] * gk[1]); o.y = cvt_pk_bf16(s[2 * 33] * gk[2], s[3 * 33] * gk[3]); o.z = cvt_pk_bf16(s[4 * 33] * gk[4], s[5 * 33] * gk[5]); o.w = cvt_pk_bf16(s[6 * 33] * gk[6], s[7 * 33] * gk[7]);
;         *(GAS v4u*)(WT + (size_t)(nd0 + n) * K + k0 + 8 * c) = o; }
	v_cvt_pk_bf16_f32 v176, v38, v39
	v_cvt_pk_bf16_f32 v177, v40, v41
	v_cvt_pk_bf16_f32 v178, v42, v43
	v_cvt_pk_bf16_f32 v179, v44, v45
	global_store_dwordx4 v67, v[176:179], s[28:29] nt
	s_mov_b32 s16, s10
	s_lshr_b32 s20, s16, 6
	s_and_b32 s24, s16, 63
	s_lshl_b32 s20, s20, 20
	s_lshl_b32 s24, s24, 7
	s_add_i32 s20, s20, s24
	s_add_i32 s20, s20, 0x3000000
	s_add_u32 s26, s0, s20
	s_addc_u32 s27, s1, 0
	global_load_dwordx4 v[142:145], v20, s[26:27] nt
	global_load_dwordx4 v[146:149], v21, s[26:27] nt
	global_load_dwordx4 v[150:153], v22, s[26:27] nt
	global_load_dwordx4 v[154:157], v23, s[26:27] nt
	global_load_dwordx4 v[158:161], v24, s[26:27] nt
	global_load_dwordx4 v[162:165], v25, s[26:27] nt
	global_load_dwordx4 v[196:199], v26, s[26:27] nt
	global_load_dwordx4 v[200:203], v27, s[26:27] nt
	global_load_dwordx4 v[204:207], v28, s[26:27] nt
	global_load_dwordx4 v[208:211], v29, s[26:27] nt
	global_load_dwordx4 v[212:215], v30, s[26:27] nt
	global_load_dwordx4 v[216:219], v31, s[26:27] nt
	global_load_dwordx4 v[228:231], v32, s[26:27] nt
	global_load_dwordx4 v[232:235], v33, s[26:27] nt
	global_load_dwordx4 v[236:239], v34, s[26:27] nt
	global_load_dwordx4 v[240:243], v35, s[26:27] nt
	s_add_i32 s16, s10, 0x800
	s_lshr_b32 s20, s16, 6
	s_and_b32 s24, s16, 63
	s_mul_i32 s24, s24, 0x60000
	s_lshl_b32 s20, s20, 8
	s_add_i32 s20, s20, s24
	s_add_i32 s20, s20, 0x3000000
	s_add_u32 s28, s2, s20
	s_addc_u32 s29, s3, 0
	s_waitcnt vmcnt(39)
	ds_write2_b32 v36, v78, v79 offset1:1
	ds_write2_b32 v36, v80, v81 offset0:2 offset1:3
	s_waitcnt vmcnt(38)
	v_add_u32_e32 v49, 0x420, v36
	ds_write2_b32 v49, v82, v83 offset1:1
	ds_write2_b32 v49, v84, v85 offset0:2 offset1:3
	s_waitcnt vmcnt(37)
	v_add_u32_e32 v48, 0x840, v36
	ds_write2_b32 v48, v86, v87 offset1:1
	ds_write2_b32 v48, v88, v89 offset0:2 offset1:3
	s_waitcnt vmcnt(36)
	v_add_u32_e32 v49, 0xc60, v36
	ds_write2_b32 v49, v90, v91 offset1:1
	ds_write2_b32 v49, v92, v93 offset0:2 offset1:3
	s_waitcnt vmcnt(35)
	v_add_u32_e32 v48, 0x1080, v36
	ds_write2_b32 v48, v94, v95 offset1:1
	ds_write2_b32 v48, v96, v97 offset0:2 offset1:3
	s_waitcnt vmcnt(34)
	v_add_u32_e32 v49, 0x14a0, v36
	ds_write2_b32 v49, v98, v99 offset1:1
	ds_write2_b32 v49, v100, v101 offset0:2 offset1:3
	s_waitcnt vmcnt(33)
	v_add_u32_e32 v48, 0x18c0, v36
	ds_write2_b32 v48, v102, v103 offset1:1
	ds_write2_b32 v48, v104, v105 offset0:2 offset1:3
	s_waitcnt vmcnt(32)
	v_add_u32_e32 v49, 0x1ce0, v36
	ds_write2_b32 v49, v106, v107 offset1:1
	ds_write2_b32 v49, v108, v109 offset0:2 offset1:3
	s_waitcnt vmcnt(31)
	v_add_u32_e32 v48, 0x2100, v36
	ds_write2_b32 v48, v110, v111 offset1:1
	ds_write2_b32 v48, v112, v113 offset0:2 offset1:3
	s_waitcnt vmcnt(30)
	v_add_u32_e32 v49, 0x2520, v36
	ds_write2_b32 v49, v114, v115 offset1:1
	ds_write2_b32 v49, v116, v117 offset0:2 offset1:3
	s_waitcnt vmcnt(29)
	v_add_u32_e32 v48, 0x2940, v36
	ds_write2_b32 v48, v118, v119 offset1:1
	ds_write2_b32 v48, v120, v121 offset0:2 offset1:3
	s_waitcnt vmcnt(28)
	v_add_u32_e32 v49, 0x2d60, v36
	ds_write2_b32 v49, v122, v123 offset1:1
	ds_write2_b32 v49, v124, v125 offset0:2 offset1:3
	s_waitcnt vmcnt(27)
	v_add_u32_e32 v48, 0x3180, v36
	ds_write2_b32 v48, v126, v127 offset1:1
	ds_write2_b32 v48, v128, v129 offset0:2 offset1:3
	s_waitcnt vmcnt(26)
	v_add_u32_e32 v49, 0x35a0, v36
	ds_write2_b32 v49, v130, v131 offset1:1
	ds_write2_b32 v49, v132, v133 offset0:2 offset1:3
	s_waitcnt vmcnt(25)
	v_add_u32_e32 v48, 0x39c0, v36
	ds_write2_b32 v48, v134, v135 offset1:1
	ds_write2_b32 v48, v136, v137 offset0:2 offset1:3
	s_waitcnt vmcnt(24)
	v_add_u32_e32 v49, 0x3de0, v36
	ds_write2_b32 v49, v138, v139 offset1:1
	ds_write2_b32 v49, v140, v141 offset0:2 offset1:3
	ds_read2_b32 v[244:245], v52 offset0:0 offset1:33
	ds_read2_b32 v[246:247], v52 offset0:66 offset1:99
	ds_read2_b32 v[248:249], v52 offset0:132 offset1:165
	ds_read2_b32 v[250:251], v52 offset0:198 offset1:231
	ds_read2_b32 v[38:39], v53 offset0:0 offset1:33
	ds_read2_b32 v[40:41], v53 offset0:66 offset1:99
	ds_read2_b32 v[42:43], v53 offset0:132 offset1:165
	ds_read2_b32 v[44:45], v53 offset0:198 offset1:231
	s_waitcnt lgkmcnt(4)
	v_cvt_pk_bf16_f32 v170, v244, v245
	v_cvt_pk_bf16_f32 v171, v246, v247
	v_cvt_pk_bf16_f32 v172, v248, v249
	v_cvt_pk_bf16_f32 v173, v250, v251
	global_store_dwordx4 v60, v[170:173], s[28:29] nt
	ds_read2_b32 v[244:245], v54 offset0:0 offset1:33
	ds_read2_b32 v[246:247], v54 offset0:66 offset1:99
	ds_read2_b32 v[248:249], v54 offset0:132 offset1:165
	ds_read2_b32 v[250:251], v54 offset0:198 offset1:231
	s_waitcnt lgkmcnt(4)
	v_cvt_pk_bf16_f32 v176, v38, v39
	v_cvt_pk_bf16_f32 v177, v40, v41
	v_cvt_pk_bf16_f32 v178, v42, v43
	v_cvt_pk_bf16_f32 v179, v44, v45
	global_store_dwordx4 v61, v[176:179], s[28:29] nt
	ds_read2_b32 v[38:39], v55 offset0:0 offset1:33
	ds_read2_b32 v[40:41], v55 offset0:66 offset1:99
	ds_read2_b32 v[42:43], v55 offset0:132 offset1:165
	ds_read2_b32 v[44:45], v55 offset0:198 offset1:231
	s_waitcnt lgkmcnt(4)
	v_cvt_pk_bf16_f32 v170, v244, v245
	v_cvt_pk_bf16_f32 v171, v246, v247
	v_cvt_pk_bf16_f32 v172, v248, v249
	v_cvt_pk_bf16_f32 v173, v250, v251
	global_store_dwordx4 v62, v[170:173], s[28:29] nt
	ds_read2_b32 v[244:245], v56 offset0:0 offset1:33
	ds_read2_b32 v[246:247], v56 offset0:66 offset1:99
	ds_read2_b32 v[248:249], v56 offset0:132 offset1:165
	ds_read2_b32 v[250:251], v56 offset0:198 offset1:231
	s_waitcnt lgkmcnt(4)
	v_cvt_pk_bf16_f32 v176, v38, v39
	v_cvt_pk_bf16_f32 v177, v40, v41
	v_cvt_pk_bf16_f32 v178, v42, v43
	v_cvt_pk_bf16_f32 v179, v44, v45
	global_store_dwordx4 v63, v[176:179], s[28:29] nt
	ds_read2_b32 v[38:39], v57 offset0:0 offset1:33
	ds_read2_b32 v[40:41], v57 offset0:66 offset1:99
	ds_read2_b32 v[42:43], v57 offset0:132 offset1:165
	ds_read2_b32 v[44:45], v57 offset0:198 offset1:231
	s_waitcnt lgkmcnt(4)
; __device__ __forceinline__ unsigned cvt_pk_bf16(float lo, float hi) { unsigned r; asm volatile("v_cvt_pk_bf16_f32 %0, %1, %2" : "=v"(r) : "v"(lo), "v"(hi)); return r; }
; #define GAS __attribute__((address_space(1)))
; #define LAS __attribute__((address_space(3)))
; #define LDS_WAIT() asm volatile("s_waitcnt lgkmcnt(0)" ::: "memory")
;     ...
;     for (int i = 0; i < 64; ++i) { const int kk = 2 * i + (lane >> 5); scr[kk * 33 + (lane & 31)] = W[(size_t)(k0 + kk) * N + n0 + (lane & 31)]; }
;     LDS_WAIT(); asm volatile("" ::: "memory");
;     const int c = lane & 15;
;     float gk[8];
;     if (gain) load8f(gain + k0 + 8 * c, gk); else {
; #pragma unroll
;         for (int e = 0; e < 8; ++e) gk[e] = 1.0f; }
; #pragma unroll
;     for (int j = 0; j < 8; ++j) { const int n = (lane >> 4) + 4 * j; const LAS float* s = scr + (8 * c) * 33 + n;
;         v4u o; o.x = cvt_pk_bf16(s[0 * 33] * gk[0], s[1 * 33] * gk[1]); o.y = cvt_pk_bf16(s[2 * 33] * gk[2], s[3 * 33] * gk[3]); o.z = cvt_pk_bf16(s[4 * 33] * gk[4], s[5 * 33] * gk[5]); o.w = cvt_pk_bf16(s[6 * 33] * gk[6], s[7 * 33] * gk[7]);
;         *(GAS v4u*)(WT + (size_t)(nd0 + n) * K + k0 + 8 * c) = o; }
	v_cvt_pk_bf16_f32 v170, v244, v245
	v_cvt_pk_bf16_f32 v171, v246, v247
	v_cvt_pk_bf16_f32 v172, v248, v249
	v_cvt_pk_bf16_f32 v173, v250, v251
	global_store_dwordx4 v64, v[170:173], s[28:29] nt
	ds_read2_b32 v[244:245], v58 offset0:0 offset1:33
	ds_read2_b32 v[246:247], v58 offset0:66 offset1:99
	ds_read2_b32 v[248:249], v58 offset0:132 offset1:165
	ds_read2_b32 v[250:251], v58 offset0:198 offset1:231
	s_waitcnt lgkmcnt(4)
	v_cvt_pk_bf16_f32 v176, v38, v39
	v_cvt_pk_bf16_f32 v177, v40, v41
	v_cvt_pk_bf16_f32 v178, v42, v43
	v_cvt_pk_bf16_f32 v179, v44, v45
	global_store_dwordx4 v65, v[176:179], s[28:29] nt
	ds_read2_b32 v[38:39], v59 offset0:0 offset1:33
	ds_read2_b32 v[40:41], v59 offset0:66 offset1:99
	ds_read2_b32 v[42:43], v59 offset0:132 offset1:165
	ds_read2_b32 v[44:45], v59 offset0:198 offset1:231
	s_waitcnt lgkmcnt(4)
	v_cvt_pk_bf16_f32 v170, v244, v245
	v_cvt_pk_bf16_f32 v171, v246, v247
	v_cvt_pk_bf16_f32 v172, v248, v249
	v_cvt_pk_bf16_f32 v173, v250, v251
	global_store_dwordx4 v66, v[170:173], s[28:29] nt
	s_waitcnt lgkmcnt(0)
	v_cvt_pk_bf16_f32 v176, v38, v39
	v_cvt_pk_bf16_f32 v177, v40, v41
	v_cvt_pk_bf16_f32 v178, v42, v43
	v_cvt_pk_bf16_f32 v179, v44, v45
	global_store_dwordx4 v67, v[176:179], s[28:29] nt
	s_add_i32 s16, s10, 0x400
	s_lshr_b32 s20, s16, 6
	s_and_b32 s24, s16, 63
	s_lshl_b32 s20, s20, 20
	s_lshl_b32 s24, s24, 7
	s_add_i32 s20, s20, s24
	s_add_i32 s20, s20, 0x3000000
	s_add_u32 s26, s0, s20
	s_addc_u32 s27, s1, 0
	global_load_dwordx4 v[78:81], v20, s[26:27] nt
	global_load_dwordx4 v[82:85], v21, s[26:27] nt
	global_load_dwordx4 v[86:89], v22, s[26:27] nt
	global_load_dwordx4 v[90:93], v23, s[26:27] nt
	global_load_dwordx4 v[94:97], v24, s[26:27] nt
	global_load_dwordx4 v[98:101], v25, s[26:27] nt
	global_load_dwordx4 v[102:105], v26, s[26:27] nt
	global_load_dwordx4 v[106:109], v27, s[26:27] nt
	global_load_dwordx4 v[110:113], v28, s[26:27] nt
	global_load_dwordx4 v[114:117], v29, s[26:27] nt
	global_load_dwordx4 v[118:121], v30, s[26:27] nt
	global_load_dwordx4 v[122:125], v31, s[26:27] nt
	global_load_dwordx4 v[126:129], v32, s[26:27] nt
	global_load_dwordx4 v[130:133], v33, s[26:27] nt
	global_load_dwordx4 v[134:137], v34, s[26:27] nt
	global_load_dwordx4 v[138:141], v35, s[26:27] nt
	s_mov_b32 s16, s10
	s_lshr_b32 s20, s16, 6
	s_and_b32 s24, s16, 63
	s_mul_i32 s24, s24, 0x60000
	s_lshl_b32 s20, s20, 8
	s_add_i32 s20, s20, s24
	s_add_i32 s20, s20, 0x1800000
	s_add_u32 s28, s2, s20
	s_addc_u32 s29, s3, 0
	s_waitcnt vmcnt(39)
	ds_write2_b32 v36, v142, v143 offset1:1
	ds_write2_b32 v36, v144, v145 offset0:2 offset1:3
	s_waitcnt vmcnt(38)
	v_add_u32_e32 v49, 0x420, v36
	ds_write2_b32 v49, v146, v147 offset1:1
	ds_write2_b32 v49, v148, v149 offset0:2 offset1:3
	s_waitcnt vmcnt(37)
	v_add_u32_e32 v48, 0x840, v36
	ds_write2_b32 v48, v150, v151 offset1:1
	ds_write2_b32 v48, v152, v153 offset0:2 offset1:3
	s_waitcnt vmcnt(36)
	v_add_u32_e32 v49, 0xc60, v36
	ds_write2_b32 v49, v154, v155 offset1:1
	ds_write2_b32 v49, v156, v157 offset0:2 offset1:3
	s_waitcnt vmcnt(35)
	v_add_u32_e32 v48, 0x1080, v36
	ds_write2_b32 v48, v158, v159 offset1:1
	ds_write2_b32 v48, v160, v161 offset0:2 offset1:3
	s_waitcnt vmcnt(34)
	v_add_u32_e32 v49, 0x14a0, v36
	ds_write2_b32 v49, v162, v163 offset1:1
	ds_write2_b32 v49, v164, v165 offset0:2 offset1:3
	s_waitcnt vmcnt(33)
	v_add_u32_e32 v48, 0x18c0, v36
	ds_write2_b32 v48, v196, v197 offset1:1
	ds_write2_b32 v48, v198, v199 offset0:2 offset1:3
	s_waitcnt vmcnt(32)
	v_add_u32_e32 v49, 0x1ce0, v36
	ds_write2_b32 v49, v200, v201 offset1:1
	ds_write2_b32 v49, v202, v203 offset0:2 offset1:3
	s_waitcnt vmcnt(31)
	v_add_u32_e32 v48, 0x2100, v36
	ds_write2_b32 v48, v204, v205 offset1:1
	ds_write2_b32 v48, v206, v207 offset0:2 offset1:3
	s_waitcnt vmcnt(30)
	v_add_u32_e32 v49, 0x2520, v36
	ds_write2_b32 v49, v208, v209 offset1:1
	ds_write2_b32 v49, v210, v211 offset0:2 offset1:3
	s_waitcnt vmcnt(29)
	v_add_u32_e32 v48, 0x2940, v36
	ds_write2_b32 v48, v212, v213 offset1:1
	ds_write2_b32 v48, v214, v215 offset0:2 offset1:3
	s_waitcnt vmcnt(28)
	v_add_u32_e32 v49, 0x2d60, v36
	ds_write2_b32 v49, v216, v217 offset1:1
	ds_write2_b32 v49, v218, v219 offset0:2 offset1:3
	s_waitcnt vmcnt(27)
	v_add_u32_e32 v48, 0x3180, v36
	ds_write2_b32 v48, v228, v229 offset1:1
	ds_write2_b32 v48, v230, v231 offset0:2 offset1:3
	s_waitcnt vmcnt(26)
	v_add_u32_e32 v49, 0x35a0, v36
	ds_write2_b32 v49, v232, v233 offset1:1
	ds_write2_b32 v49, v234, v235 offset0:2 offset1:3
	s_waitcnt vmcnt(25)
	v_add_u32_e32 v48, 0x39c0, v36
	ds_write2_b32 v48, v236, v237 offset1:1
	ds_write2_b32 v48, v238, v239 offset0:2 offset1:3
	s_waitcnt vmcnt(24)
	v_add_u32_e32 v49, 0x3de0, v36
	ds_write2_b32 v49, v240, v241 offset1:1
	ds_write2_b32 v49, v242, v243 offset0:2 offset1:3
	ds_read2_b32 v[244:245], v52 offset0:0 offset1:33
	ds_read2_b32 v[246:247], v52 offset0:66 offset1:99
	ds_read2_b32 v[248:249], v52 offset0:132 offset1:165
	ds_read2_b32 v[250:251], v52 offset0:198 offset1:231
	ds_read2_b32 v[38:39], v53 offset0:0 offset1:33
	ds_read2_b32 v[40:41], v53 offset0:66 offset1:99
	ds_read2_b32 v[42:43], v53 offset0:132 offset1:165
	ds_read2_b32 v[44:45], v53 offset0:198 offset1:231
	s_waitcnt lgkmcnt(4)
	v_cvt_pk_bf16_f32 v170, v244, v245
	v_cvt_pk_bf16_f32 v171, v246, v247
	v_cvt_pk_bf16_f32 v172, v248, v249
	v_cvt_pk_bf16_f32 v173, v250, v251
	global_store_dwordx4 v60, v[170:173], s[28:29] nt
	ds_read2_b32 v[244:245], v54 offset0:0 offset1:33
	ds_read2_b32 v[246:247], v54 offset0:66 offset1:99
	ds_read2_b32 v[248:249], v54 offset0:132 offset1:165
	ds_read2_b32 v[250:251], v54 offset0:198 offset1:231
	s_waitcnt lgkmcnt(4)
; __device__ __forceinline__ unsigned cvt_pk_bf16(float lo, float hi) { unsigned r; asm volatile("v_cvt_pk_bf16_f32 %0, %1, %2" : "=v"(r) : "v"(lo), "v"(hi)); return r; }
; #define GAS __attribute__((address_space(1)))
; #define LAS __attribute__((address_space(3)))
; #define LDS_WAIT() asm volatile("s_waitcnt lgkmcnt(0)" ::: "memory")
;     ...
;     for (int i = 0; i < 64; ++i) { const int kk = 2 * i + (lane >> 5); scr[kk * 33 + (lane & 31)] = W[(size_t)(k0 + kk) * N + n0 + (lane & 31)]; }
;     LDS_WAIT(); asm volatile("" ::: "memory");
;     const int c = lane & 15;
;     float gk[8];
;     if (gain) load8f(gain + k0 + 8 * c, gk); else {
; #pragma unroll
;         for (int e = 0; e < 8; ++e) gk[e] = 1.0f; }
; #pragma unroll
;     for (int j = 0; j < 8; ++j) { const int n = (lane >> 4) + 4 * j; const LAS float* s = scr + (8 * c) * 33 + n;
;         v4u o; o.x = cvt_pk_bf16(s[0 * 33] * gk[0], s[1 * 33] * gk[1]); o.y = cvt_pk_bf16(s[2 * 33] * gk[2], s[3 * 33] * gk[3]); o.z = cvt_pk_bf16(s[4 * 33] * gk[4], s[5 * 33] * gk[5]); o.w = cvt_pk_bf16(s[6 * 33] * gk[6], s[7 * 33] * gk[7]);
;         *(GAS v4u*)(WT + (size_t)(nd0 + n) * K + k0 + 8 * c) = o; }
	v_cvt_pk_bf16_f32 v176, v38, v39
	v_cvt_pk_bf16_f32 v177, v40, v41
	v_cvt_pk_bf16_f32 v178, v42, v43
	v_cvt_pk_bf16_f32 v179, v44, v45
	global_store_dwordx4 v61, v[176:179], s[28:29] nt
	ds_read2_b32 v[38:39], v55 offset0:0 offset1:33
	ds_read2_b32 v[40:41], v55 offset0:66 offset1:99
	ds_read2_b32 v[42:43], v55 offset0:132 offset1:165
	ds_read2_b32 v[44:45], v55 offset0:198 offset1:231
	s_waitcnt lgkmcnt(4)
	v_cvt_pk_bf16_f32 v170, v244, v245
	v_cvt_pk_bf16_f32 v171, v246, v247
	v_cvt_pk_bf16_f32 v172, v248, v249
	v_cvt_pk_bf16_f32 v173, v250, v251
	global_store_dwordx4 v62, v[170:173], s[28:29] nt
	ds_read2_b32 v[244:245], v56 offset0:0 offset1:33
	ds_read2_b32 v[246:247], v56 offset0:66 offset1:99
	ds_read2_b32 v[248:249], v56 offset0:132 offset1:165
	ds_read2_b32 v[250:251], v56 offset0:198 offset1:231
	s_waitcnt lgkmcnt(4)
	v_cvt_pk_bf16_f32 v176, v38, v39
	v_cvt_pk_bf16_f32 v177, v40, v41
	v_cvt_pk_bf16_f32 v178, v42, v43
	v_cvt_pk_bf16_f32 v179, v44, v45
	global_store_dwordx4 v63, v[176:179], s[28:29] nt
	ds_read2_b32 v[38:39], v57 offset0:0 offset1:33
	ds_read2_b32 v[40:41], v57 offset0:66 offset1:99
	ds_read2_b32 v[42:43], v57 offset0:132 offset1:165
	ds_read2_b32 v[44:45], v57 offset0:198 offset1:231
	s_waitcnt lgkmcnt(4)
	v_cvt_pk_bf16_f32 v170, v244, v245
	v_cvt_pk_bf16_f32 v171, v246, v247
	v_cvt_pk_bf16_f32 v172, v248, v249
	v_cvt_pk_bf16_f32 v173, v250, v251
	global_store_dwordx4 v64, v[170:173], s[28:29] nt
	ds_read2_b32 v[244:245], v58 offset0:0 offset1:33
	ds_read2_b32 v[246:247], v58 offset0:66 offset1:99
	ds_read2_b32 v[248:249], v58 offset0:132 offset1:165
	ds_read2_b32 v[250:251], v58 offset0:198 offset1:231
	s_waitcnt lgkmcnt(4)
	v_cvt_pk_bf16_f32 v176, v38, v39
	v_cvt_pk_bf16_f32 v177, v40, v41
	v_cvt_pk_bf16_f32 v178, v42, v43
	v_cvt_pk_bf16_f32 v179, v44, v45
	global_store_dwordx4 v65, v[176:179], s[28:29] nt
	ds_read2_b32 v[38:39], v59 offset0:0 offset1:33
	ds_read2_b32 v[40:41], v59 offset0:66 offset1:99
	ds_read2_b32 v[42:43], v59 offset0:132 offset1:165
	ds_read2_b32 v[44:45], v59 offset0:198 offset1:231
	s_waitcnt lgkmcnt(4)
	v_cvt_pk_bf16_f32 v170, v244, v245
	v_cvt_pk_bf16_f32 v171, v246, v247
	v_cvt_pk_bf16_f32 v172, v248, v249
	v_cvt_pk_bf16_f32 v173, v250, v251
	global_store_dwordx4 v66, v[170:173], s[28:29] nt
	s_waitcnt lgkmcnt(0)
	v_cvt_pk_bf16_f32 v176, v38, v39
	v_cvt_pk_bf16_f32 v177, v40, v41
	v_cvt_pk_bf16_f32 v178, v42, v43
	v_cvt_pk_bf16_f32 v179, v44, v45
	global_store_dwordx4 v67, v[176:179], s[28:29] nt
	s_add_i32 s16, s10, 0x800
	s_lshr_b32 s20, s16, 6
	s_and_b32 s24, s16, 63
	s_lshl_b32 s20, s20, 20
	s_lshl_b32 s24, s24, 7
	s_add_i32 s20, s20, s24
	s_add_i32 s20, s20, 0x3000000
	s_add_u32 s26, s0, s20
	s_addc_u32 s27, s1, 0
	global_load_dwordx4 v[142:145], v20, s[26:27] nt
	global_load_dwordx4 v[146:149], v21, s[26:27] nt
	global_load_dwordx4 v[150:153], v22, s[26:27] nt
	global_load_dwordx4 v[154:157], v23, s[26:27] nt
	global_load_dwordx4 v[158:161], v24, s[26:27] nt
	global_load_dwordx4 v[162:165], v25, s[26:27] nt
	global_load_dwordx4 v[196:199], v26, s[26:27] nt
	global_load_dwordx4 v[200:203], v27, s[26:27] nt
	global_load_dwordx4 v[204:207], v28, s[26:27] nt
	global_load_dwordx4 v[208:211], v29, s[26:27] nt
	global_load_dwordx4 v[212:215], v30, s[26:27] nt
	global_load_dwordx4 v[216:219], v31, s[26:27] nt
	global_load_dwordx4 v[228:231], v32, s[26:27] nt
	global_load_dwordx4 v[232:235], v33, s[26:27] nt
	global_load_dwordx4 v[236:239], v34, s[26:27] nt
	global_load_dwordx4 v[240:243], v35, s[26:27] nt
	s_add_i32 s16, s10, 0x400
	s_lshr_b32 s20, s16, 6
	s_and_b32 s24, s16, 63
	s_mul_i32 s24, s24, 0x60000
	s_lshl_b32 s20, s20, 8
	s_add_i32 s20, s20, s24
	s_add_i32 s20, s20, 0x1800000
	s_add_u32 s28, s2, s20
	s_addc_u32 s29, s3, 0
	s_waitcnt vmcnt(39)
	ds_write2_b32 v36, v78, v79 offset1:1
	ds_write2_b32 v36, v80, v81 offset0:2 offset1:3
	s_waitcnt vmcnt(38)
	v_add_u32_e32 v49, 0x420, v36
	ds_write2_b32 v49, v82, v83 offset1:1
	ds_write2_b32 v49, v84, v85 offset0:2 offset1:3
	s_waitcnt vmcnt(37)
	v_add_u32_e32 v48, 0x840, v36
	ds_write2_b32 v48, v86, v87 offset1:1
	ds_write2_b32 v48, v88, v89 offset0:2 offset1:3
	s_waitcnt vmcnt(36)
	v_add_u32_e32 v49, 0xc60, v36
	ds_write2_b32 v49, v90, v91 offset1:1
	ds_write2_b32 v49, v92, v93 offset0:2 offset1:3
	s_waitcnt vmcnt(35)
	v_add_u32_e32 v48, 0x1080, v36
	ds_write2_b32 v48, v94, v95 offset1:1
	ds_write2_b32 v48, v96, v97 offset0:2 offset1:3
	s_waitcnt vmcnt(34)
	v_add_u32_e32 v49, 0x14a0, v36
	ds_write2_b32 v49, v98, v99 offset1:1
	ds_write2_b32 v49, v100, v101 offset0:2 offset1:3
	s_waitcnt vmcnt(33)
	v_add_u32_e32 v48, 0x18c0, v36
	ds_write2_b32 v48, v102, v103 offset1:1
	ds_write2_b32 v48, v104, v105 offset0:2 offset1:3
	s_waitcnt vmcnt(32)
	v_add_u32_e32 v49, 0x1ce0, v36
	ds_write2_b32 v49, v106, v107 offset1:1
	ds_write2_b32 v49, v108, v109 offset0:2 offset1:3
	s_waitcnt vmcnt(31)
	v_add_u32_e32 v48, 0x2100, v36
	ds_write2_b32 v48, v110, v111 offset1:1
	ds_write2_b32 v48, v112, v113 offset0:2 offset1:3
	s_waitcnt vmcnt(30)
	v_add_u32_e32 v49, 0x2520, v36
	ds_write2_b32 v49, v114, v115 offset1:1
	ds_write2_b32 v49, v116, v117 offset0:2 offset1:3
	s_waitcnt vmcnt(29)
	v_add_u32_e32 v48, 0x2940, v36
	ds_write2_b32 v48, v118, v119 offset1:1
	ds_write2_b32 v48, v120, v121 offset0:2 offset1:3
	s_waitcnt vmcnt(28)
	v_add_u32_e32 v49, 0x2d60, v36
	ds_write2_b32 v49, v122, v123 offset1:1
	ds_write2_b32 v49, v124, v125 offset0:2 offset1:3
	s_waitcnt vmcnt(27)
	v_add_u32_e32 v48, 0x3180, v36
	ds_write2_b32 v48, v126, v127 offset1:1
	ds_write2_b32 v48, v128, v129 offset0:2 offset1:3
	s_waitcnt vmcnt(26)
; __device__ __forceinline__ unsigned cvt_pk_bf16(float lo, float hi) { unsigned r; asm volatile("v_cvt_pk_bf16_f32 %0, %1, %2" : "=v"(r) : "v"(lo), "v"(hi)); return r; }
; #define GAS __attribute__((address_space(1)))
; #define LAS __attribute__((address_space(3)))
; #define LDS_WAIT() asm volatile("s_waitcnt lgkmcnt(0)" ::: "memory")
;     ...
;     for (int i = 0; i < 64; ++i) { const int kk = 2 * i + (lane >> 5); scr[kk * 33 + (lane & 31)] = W[(size_t)(k0 + kk) * N + n0 + (lane & 31)]; }
;     LDS_WAIT(); asm volatile("" ::: "memory");
;     const int c = lane & 15;
;     float gk[8];
;     if (gain) load8f(gain + k0 + 8 * c, gk); else {
; #pragma unroll
;         for (int e = 0; e < 8; ++e) gk[e] = 1.0f; }
; #pragma unroll
;     for (int j = 0; j < 8; ++j) { const int n = (lane >> 4) + 4 * j; const LAS float* s = scr + (8 * c) * 33 + n;
;         v4u o; o.x = cvt_pk_bf16(s[0 * 33] * gk[0], s[1 * 33] * gk[1]); o.y = cvt_pk_bf16(s[2 * 33] * gk[2], s[3 * 33] * gk[3]); o.z = cvt_pk_bf16(s[4 * 33] * gk[4], s[5 * 33] * gk[5]); o.w = cvt_pk_bf16(s[6 * 33] * gk[6], s[7 * 33] * gk[7]);
;         *(GAS v4u*)(WT + (size_t)(nd0 + n) * K + k0 + 8 * c) = o; }
	v_add_u32_e32 v49, 0x35a0, v36
	ds_write2_b32 v49, v130, v131 offset1:1
	ds_write2_b32 v49, v132, v133 offset0:2 offset1:3
	s_waitcnt vmcnt(25)
	v_add_u32_e32 v48, 0x39c0, v36
	ds_write2_b32 v48, v134, v135 offset1:1
	ds_write2_b32 v48, v136, v137 offset0:2 offset1:3
	s_waitcnt vmcnt(24)
	v_add_u32_e32 v49, 0x3de0, v36
	ds_write2_b32 v49, v138, v139 offset1:1
	ds_write2_b32 v49, v140, v141 offset0:2 offset1:3
	ds_read2_b32 v[244:245], v52 offset0:0 offset1:33
	ds_read2_b32 v[246:247], v52 offset0:66 offset1:99
	ds_read2_b32 v[248:249], v52 offset0:132 offset1:165
	ds_read2_b32 v[250:251], v52 offset0:198 offset1:231
	ds_read2_b32 v[38:39], v53 offset0:0 offset1:33
	ds_read2_b32 v[40:41], v53 offset0:66 offset1:99
	ds_read2_b32 v[42:43], v53 offset0:132 offset1:165
	ds_read2_b32 v[44:45], v53 offset0:198 offset1:231
	s_waitcnt lgkmcnt(4)
	v_cvt_pk_bf16_f32 v170, v244, v245
	v_cvt_pk_bf16_f32 v171, v246, v247
	v_cvt_pk_bf16_f32 v172, v248, v249
	v_cvt_pk_bf16_f32 v173, v250, v251
	global_store_dwordx4 v60, v[170:173], s[28:29] nt
	ds_read2_b32 v[244:245], v54 offset0:0 offset1:33
	ds_read2_b32 v[246:247], v54 offset0:66 offset1:99
	ds_read2_b32 v[248:249], v54 offset0:132 offset1:165
	ds_read2_b32 v[250:251], v54 offset0:198 offset1:231
	s_waitcnt lgkmcnt(4)
	v_cvt_pk_bf16_f32 v176, v38, v39
	v_cvt_pk_bf16_f32 v177, v40, v41
	v_cvt_pk_bf16_f32 v178, v42, v43
	v_cvt_pk_bf16_f32 v179, v44, v45
	global_store_dwordx4 v61, v[176:179], s[28:29] nt
	ds_read2_b32 v[38:39], v55 offset0:0 offset1:33
	ds_read2_b32 v[40:41], v55 offset0:66 offset1:99
	ds_read2_b32 v[42:43], v55 offset0:132 offset1:165
	ds_read2_b32 v[44:45], v55 offset0:198 offset1:231
	s_waitcnt lgkmcnt(4)
	v_cvt_pk_bf16_f32 v170, v244, v245
	v_cvt_pk_bf16_f32 v171, v246, v247
	v_cvt_pk_bf16_f32 v172, v248, v249
	v_cvt_pk_bf16_f32 v173, v250, v251
	global_store_dwordx4 v62, v[170:173], s[28:29] nt
	ds_read2_b32 v[244:245], v56 offset0:0 offset1:33
	ds_read2_b32 v[246:247], v56 offset0:66 offset1:99
	ds_read2_b32 v[248:249], v56 offset0:132 offset1:165
	ds_read2_b32 v[250:251], v56 offset0:198 offset1:231
	s_waitcnt lgkmcnt(4)
	v_cvt_pk_bf16_f32 v176, v38, v39
	v_cvt_pk_bf16_f32 v177, v40, v41
	v_cvt_pk_bf16_f32 v178, v42, v43
	v_cvt_pk_bf16_f32 v179, v44, v45
	global_store_dwordx4 v63, v[176:179], s[28:29] nt
	ds_read2_b32 v[38:39], v57 offset0:0 offset1:33
	ds_read2_b32 v[40:41], v57 offset0:66 offset1:99
	ds_read2_b32 v[42:43], v57 offset0:132 offset1:165
	ds_read2_b32 v[44:45], v57 offset0:198 offset1:231
	s_waitcnt lgkmcnt(4)
	v_cvt_pk_bf16_f32 v170, v244, v245
	v_cvt_pk_bf16_f32 v171, v246, v247
	v_cvt_pk_bf16_f32 v172, v248, v249
	v_cvt_pk_bf16_f32 v173, v250, v251
	global_store_dwordx4 v64, v[170:173], s[28:29] nt
	ds_read2_b32 v[244:245], v58 offset0:0 offset1:33
	ds_read2_b32 v[246:247], v58 offset0:66 offset1:99
	ds_read2_b32 v[248:249], v58 offset0:132 offset1:165
	ds_read2_b32 v[250:251], v58 offset0:198 offset1:231
	s_waitcnt lgkmcnt(4)
	v_cvt_pk_bf16_f32 v176, v38, v39
	v_cvt_pk_bf16_f32 v177, v40, v41
	v_cvt_pk_bf16_f32 v178, v42, v43
	v_cvt_pk_bf16_f32 v179, v44, v45
	global_store_dwordx4 v65, v[176:179], s[28:29] nt
	ds_read2_b32 v[38:39], v59 offset0:0 offset1:33
	ds_read2_b32 v[40:41], v59 offset0:66 offset1:99
	ds_read2_b32 v[42:43], v59 offset0:132 offset1:165
	ds_read2_b32 v[44:45], v59 offset0:198 offset1:231
	s_waitcnt lgkmcnt(4)
	v_cvt_pk_bf16_f32 v170, v244, v245
	v_cvt_pk_bf16_f32 v171, v246, v247
	v_cvt_pk_bf16_f32 v172, v248, v249
	v_cvt_pk_bf16_f32 v173, v250, v251
	global_store_dwordx4 v66, v[170:173], s[28:29] nt
	s_waitcnt lgkmcnt(0)
	v_cvt_pk_bf16_f32 v176, v38, v39
	v_cvt_pk_bf16_f32 v177, v40, v41
	v_cvt_pk_bf16_f32 v178, v42, v43
	v_cvt_pk_bf16_f32 v179, v44, v45
	global_store_dwordx4 v67, v[176:179], s[28:29] nt
	s_add_i32 s16, s10, 0x800
	s_lshr_b32 s20, s16, 6
	s_and_b32 s24, s16, 63
	s_mul_i32 s24, s24, 0x60000
	s_lshl_b32 s20, s20, 8
	s_add_i32 s20, s20, s24
	s_add_i32 s20, s20, 0x1800000
	s_add_u32 s28, s2, s20
	s_addc_u32 s29, s3, 0
	s_waitcnt vmcnt(23)
	ds_write2_b32 v36, v142, v143 offset1:1
	ds_write2_b32 v36, v144, v145 offset0:2 offset1:3
	s_waitcnt vmcnt(22)
	v_add_u32_e32 v49, 0x420, v36
	ds_write2_b32 v49, v146, v147 offset1:1
	ds_write2_b32 v49, v148, v149 offset0:2 offset1:3
	s_waitcnt vmcnt(21)
	v_add_u32_e32 v48, 0x840, v36
	ds_write2_b32 v48, v150, v151 offset1:1
	ds_write2_b32 v48, v152, v153 offset0:2 offset1:3
	s_waitcnt vmcnt(20)
	v_add_u32_e32 v49, 0xc60, v36
	ds_write2_b32 v49, v154, v155 offset1:1
	ds_write2_b32 v49, v156, v157 offset0:2 offset1:3
	s_waitcnt vmcnt(19)
	v_add_u32_e32 v48, 0x1080, v36
	ds_write2_b32 v48, v158, v159 offset1:1
	ds_write2_b32 v48, v160, v161 offset0:2 offset1:3
	s_waitcnt vmcnt(18)
	v_add_u32_e32 v49, 0x14a0, v36
	ds_write2_b32 v49, v162, v163 offset1:1
	ds_write2_b32 v49, v164, v165 offset0:2 offset1:3
	s_waitcnt vmcnt(17)
	v_add_u32_e32 v48, 0x18c0, v36
	ds_write2_b32 v48, v196, v197 offset1:1
	ds_write2_b32 v48, v198, v199 offset0:2 offset1:3
	s_waitcnt vmcnt(16)
	v_add_u32_e32 v49, 0x1ce0, v36
	ds_write2_b32 v49, v200, v201 offset1:1
	ds_write2_b32 v49, v202, v203 offset0:2 offset1:3
	s_waitcnt vmcnt(15)
	v_add_u32_e32 v48, 0x2100, v36
	ds_write2_b32 v48, v204, v205 offset1:1
	ds_write2_b32 v48, v206, v207 offset0:2 offset1:3
	s_waitcnt vmcnt(14)
	v_add_u32_e32 v49, 0x2520, v36
	ds_write2_b32 v49, v208, v209 offset1:1
	ds_write2_b32 v49, v210, v211 offset0:2 offset1:3
	s_waitcnt vmcnt(13)
	v_add_u32_e32 v48, 0x2940, v36
	ds_write2_b32 v48, v212, v213 offset1:1
	ds_write2_b32 v48, v214, v215 offset0:2 offset1:3
	s_waitcnt vmcnt(12)
; __device__ __forceinline__ unsigned cvt_pk_bf16(float lo, float hi) { unsigned r; asm volatile("v_cvt_pk_bf16_f32 %0, %1, %2" : "=v"(r) : "v"(lo), "v"(hi)); return r; }
; #define GAS __attribute__((address_space(1)))
; #define LAS __attribute__((address_space(3)))
; #define LDS_WAIT() asm volatile("s_waitcnt lgkmcnt(0)" ::: "memory")
;     ...
;     for (int i = 0; i < 64; ++i) { const int kk = 2 * i + (lane >> 5); scr[kk * 33 + (lane & 31)] = W[(size_t)(k0 + kk) * N + n0 + (lane & 31)]; }
;     LDS_WAIT(); asm volatile("" ::: "memory");
;     const int c = lane & 15;
;     float gk[8];
;     if (gain) load8f(gain + k0 + 8 * c, gk); else {
; #pragma unroll
;         for (int e = 0; e < 8; ++e) gk[e] = 1.0f; }
; #pragma unroll
;     for (int j = 0; j < 8; ++j) { const int n = (lane >> 4) + 4 * j; const LAS float* s = scr + (8 * c) * 33 + n;
;         v4u o; o.x = cvt_pk_bf16(s[0 * 33] * gk[0], s[1 * 33] * gk[1]); o.y = cvt_pk_bf16(s[2 * 33] * gk[2], s[3 * 33] * gk[3]); o.z = cvt_pk_bf16(s[4 * 33] * gk[4], s[5 * 33] * gk[5]); o.w = cvt_pk_bf16(s[6 * 33] * gk[6], s[7 * 33] * gk[7]);
;         *(GAS v4u*)(WT + (size_t)(nd0 + n) * K + k0 + 8 * c) = o; }
	v_add_u32_e32 v49, 0x2d60, v36
	ds_write2_b32 v49, v216, v217 offset1:1
	ds_write2_b32 v49, v218, v219 offset0:2 offset1:3
	s_waitcnt vmcnt(11)
	v_add_u32_e32 v48, 0x3180, v36
	ds_write2_b32 v48, v228, v229 offset1:1
	ds_write2_b32 v48, v230, v231 offset0:2 offset1:3
	s_waitcnt vmcnt(10)
	v_add_u32_e32 v49, 0x35a0, v36
	ds_write2_b32 v49, v232, v233 offset1:1
	ds_write2_b32 v49, v234, v235 offset0:2 offset1:3
	s_waitcnt vmcnt(9)
	v_add_u32_e32 v48, 0x39c0, v36
	ds_write2_b32 v48, v236, v237 offset1:1
	ds_write2_b32 v48, v238, v239 offset0:2 offset1:3
	s_waitcnt vmcnt(8)
	v_add_u32_e32 v49, 0x3de0, v36
	ds_write2_b32 v49, v240, v241 offset1:1
	ds_write2_b32 v49, v242, v243 offset0:2 offset1:3
	ds_read2_b32 v[244:245], v52 offset0:0 offset1:33
	ds_read2_b32 v[246:247], v52 offset0:66 offset1:99
	ds_read2_b32 v[248:249], v52 offset0:132 offset1:165
	ds_read2_b32 v[250:251], v52 offset0:198 offset1:231
	ds_read2_b32 v[38:39], v53 offset0:0 offset1:33
	ds_read2_b32 v[40:41], v53 offset0:66 offset1:99
	ds_read2_b32 v[42:43], v53 offset0:132 offset1:165
	ds_read2_b32 v[44:45], v53 offset0:198 offset1:231
	s_waitcnt lgkmcnt(4)
	v_cvt_pk_bf16_f32 v170, v244, v245
	v_cvt_pk_bf16_f32 v171, v246, v247
	v_cvt_pk_bf16_f32 v172, v248, v249
	v_cvt_pk_bf16_f32 v173, v250, v251
	global_store_dwordx4 v60, v[170:173], s[28:29] nt
	ds_read2_b32 v[244:245], v54 offset0:0 offset1:33
	ds_read2_b32 v[246:247], v54 offset0:66 offset1:99
	ds_read2_b32 v[248:249], v54 offset0:132 offset1:165
	ds_read2_b32 v[250:251], v54 offset0:198 offset1:231
	s_waitcnt lgkmcnt(4)
	v_cvt_pk_bf16_f32 v176, v38, v39
	v_cvt_pk_bf16_f32 v177, v40, v41
	v_cvt_pk_bf16_f32 v178, v42, v43
	v_cvt_pk_bf16_f32 v179, v44, v45
	global_store_dwordx4 v61, v[176:179], s[28:29] nt
	ds_read2_b32 v[38:39], v55 offset0:0 offset1:33
	ds_read2_b32 v[40:41], v55 offset0:66 offset1:99
	ds_read2_b32 v[42:43], v55 offset0:132 offset1:165
	ds_read2_b32 v[44:45], v55 offset0:198 offset1:231
	s_waitcnt lgkmcnt(4)
	v_cvt_pk_bf16_f32 v170, v244, v245
	v_cvt_pk_bf16_f32 v171, v246, v247
	v_cvt_pk_bf16_f32 v172, v248, v249
	v_cvt_pk_bf16_f32 v173, v250, v251
	global_store_dwordx4 v62, v[170:173], s[28:29] nt
	ds_read2_b32 v[244:245], v56 offset0:0 offset1:33
	ds_read2_b32 v[246:247], v56 offset0:66 offset1:99
	ds_read2_b32 v[248:249], v56 offset0:132 offset1:165
	ds_read2_b32 v[250:251], v56 offset0:198 offset1:231
	s_waitcnt lgkmcnt(4)
	v_cvt_pk_bf16_f32 v176, v38, v39
	v_cvt_pk_bf16_f32 v177, v40, v41
	v_cvt_pk_bf16_f32 v178, v42, v43
	v_cvt_pk_bf16_f32 v179, v44, v45
	global_store_dwordx4 v63, v[176:179], s[28:29] nt
	ds_read2_b32 v[38:39], v57 offset0:0 offset1:33
	ds_read2_b32 v[40:41], v57 offset0:66 offset1:99
	ds_read2_b32 v[42:43], v57 offset0:132 offset1:165
	ds_read2_b32 v[44:45], v57 offset0:198 offset1:231
	s_waitcnt lgkmcnt(4)
	v_cvt_pk_bf16_f32 v170, v244, v245
	v_cvt_pk_bf16_f32 v171, v246, v247
	v_cvt_pk_bf16_f32 v172, v248, v249
	v_cvt_pk_bf16_f32 v173, v250, v251
	global_store_dwordx4 v64, v[170:173], s[28:29] nt
	ds_read2_b32 v[244:245], v58 offset0:0 offset1:33
	ds_read2_b32 v[246:247], v58 offset0:66 offset1:99
	ds_read2_b32 v[248:249], v58 offset0:132 offset1:165
	ds_read2_b32 v[250:251], v58 offset0:198 offset1:231
	s_waitcnt lgkmcnt(4)
	v_cvt_pk_bf16_f32 v176, v38, v39
	v_cvt_pk_bf16_f32 v177, v40, v41
	v_cvt_pk_bf16_f32 v178, v42, v43
	v_cvt_pk_bf16_f32 v179, v44, v45
	global_store_dwordx4 v65, v[176:179], s[28:29] nt
	ds_read2_b32 v[38:39], v59 offset0:0 offset1:33
	ds_read2_b32 v[40:41], v59 offset0:66 offset1:99
	ds_read2_b32 v[42:43], v59 offset0:132 offset1:165
	ds_read2_b32 v[44:45], v59 offset0:198 offset1:231
	s_waitcnt lgkmcnt(4)
	v_cvt_pk_bf16_f32 v170, v244, v245
	v_cvt_pk_bf16_f32 v171, v246, v247
	v_cvt_pk_bf16_f32 v172, v248, v249
	v_cvt_pk_bf16_f32 v173, v250, v251
	global_store_dwordx4 v66, v[170:173], s[28:29] nt
	s_waitcnt lgkmcnt(0)
	v_cvt_pk_bf16_f32 v176, v38, v39
	v_cvt_pk_bf16_f32 v177, v40, v41
	v_cvt_pk_bf16_f32 v178, v42, v43
	v_cvt_pk_bf16_f32 v179, v44, v45
	global_store_dwordx4 v67, v[176:179], s[28:29] nt
	s_branch .Ldfr_done
.Ldfr_p1:
	s_mov_b32 s16, s10
	s_lshr_b32 s20, s16, 6
	s_and_b32 s24, s16, 63
	s_lshl_b32 s20, s20, 20
	s_lshl_b32 s24, s24, 7
	s_add_i32 s20, s20, s24
	s_add_i32 s20, s20, 0x9000000
	s_add_u32 s26, s0, s20
	s_addc_u32 s27, s1, 0
	global_load_dwordx4 v[78:81], v20, s[26:27] nt
	global_load_dwordx4 v[82:85], v21, s[26:27] nt
	global_load_dwordx4 v[86:89], v22, s[26:27] nt
	global_load_dwordx4 v[90:93], v23, s[26:27] nt
	global_load_dwordx4 v[94:97], v24, s[26:27] nt
	global_load_dwordx4 v[98:101], v25, s[26:27] nt
	global_load_dwordx4 v[102:105], v26, s[26:27] nt
	global_load_dwordx4 v[106:109], v27, s[26:27] nt
	global_load_dwordx4 v[110:113], v28, s[26:27] nt
	global_load_dwordx4 v[114:117], v29, s[26:27] nt
	global_load_dwordx4 v[118:121], v30, s[26:27] nt
	global_load_dwordx4 v[122:125], v31, s[26:27] nt
	global_load_dwordx4 v[126:129], v32, s[26:27] nt
	global_load_dwordx4 v[130:133], v33, s[26:27] nt
	global_load_dwordx4 v[134:137], v34, s[26:27] nt
	global_load_dwordx4 v[138:141], v35, s[26:27] nt
	s_add_i32 s16, s10, 0x400
	s_lshr_b32 s20, s16, 6
	s_and_b32 s24, s16, 63
	s_lshl_b32 s20, s20, 20
	s_lshl_b32 s24, s24, 7
	s_add_i32 s20, s20, s24
	s_add_i32 s20, s20, 0x9000000
	s_add_u32 s26, s0, s20
	s_addc_u32 s27, s1, 0
	global_load_dwordx4 v[142:145], v20, s[26:27] nt
	global_load_dwordx4 v[146:149], v21, s[26:27] nt
	global_load_dwordx4 v[150:153], v22, s[26:27] nt
	global_load_dwordx4 v[154:157], v23, s[26:27] nt
	global_load_dwordx4 v[158:161], v24, s[26:27] nt
	global_load_dwordx4 v[162:165], v25, s[26:27] nt
	global_load_dwordx4 v[196:199], v26, s[26:27] nt
	global_load_dwordx4 v[200:203], v27, s[26:27] nt
	global_load_dwordx4 v[204:207], v28, s[26:27] nt
	global_load_dwordx4 v[208:211], v29, s[26:27] nt
	global_load_dwordx4 v[212:215], v30, s[26:27] nt
	global_load_dwordx4 v[216:219], v31, s[26:27] nt
	global_load_dwordx4 v[228:231], v32, s[26:27] nt
	global_load_dwordx4 v[232:235], v33, s[26:27] nt
	global_load_dwordx4 v[236:239], v34, s[26:27] nt
	global_load_dwordx4 v[240:243], v35, s[26:27] nt
	s_mov_b32 s16, s10
	s_lshr_b32 s20, s16, 6
	s_and_b32 s24, s16, 63
	s_mul_i32 s24, s24, 0x60000
	s_lshl_b32 s20, s20, 8
	s_add_i32 s20, s20, s24
	s_add_i32 s20, s20, 0x4800000
	s_add_u32 s28, s2, s20
	s_addc_u32 s29, s3, 0
	s_waitcnt vmcnt(31)
; __device__ __forceinline__ unsigned cvt_pk_bf16(float lo, float hi) { unsigned r; asm volatile("v_cvt_pk_bf16_f32 %0, %1, %2" : "=v"(r) : "v"(lo), "v"(hi)); return r; }
; #define GAS __attribute__((address_space(1)))
; #define LAS __attribute__((address_space(3)))
; #define LDS_WAIT() asm volatile("s_waitcnt lgkmcnt(0)" ::: "memory")
;     ...
;     for (int i = 0; i < 64; ++i) { const int kk = 2 * i + (lane >> 5); scr[kk * 33 + (lane & 31)] = W[(size_t)(k0 + kk) * N + n0 + (lane & 31)]; }
;     LDS_WAIT(); asm volatile("" ::: "memory");
;     const int c = lane & 15;
;     float gk[8];
;     if (gain) load8f(gain + k0 + 8 * c, gk); else {
; #pragma unroll
;         for (int e = 0; e < 8; ++e) gk[e] = 1.0f; }
; #pragma unroll
;     for (int j = 0; j < 8; ++j) { const int n = (lane >> 4) + 4 * j; const LAS float* s = scr + (8 * c) * 33 + n;
;         v4u o; o.x = cvt_pk_bf16(s[0 * 33] * gk[0], s[1 * 33] * gk[1]); o.y = cvt_pk_bf16(s[2 * 33] * gk[2], s[3 * 33] * gk[3]); o.z = cvt_pk_bf16(s[4 * 33] * gk[4], s[5 * 33] * gk[5]); o.w = cvt_pk_bf16(s[6 * 33] * gk[6], s[7 * 33] * gk[7]);
;         *(GAS v4u*)(WT + (size_t)(nd0 + n) * K + k0 + 8 * c) = o; }
	ds_write2_b32 v36, v78, v79 offset1:1
	ds_write2_b32 v36, v80, v81 offset0:2 offset1:3
	s_waitcnt vmcnt(30)
	v_add_u32_e32 v49, 0x420, v36
	ds_write2_b32 v49, v82, v83 offset1:1
	ds_write2_b32 v49, v84, v85 offset0:2 offset1:3
	s_waitcnt vmcnt(29)
	v_add_u32_e32 v48, 0x840, v36
	ds_write2_b32 v48, v86, v87 offset1:1
	ds_write2_b32 v48, v88, v89 offset0:2 offset1:3
	s_waitcnt vmcnt(28)
	v_add_u32_e32 v49, 0xc60, v36
	ds_write2_b32 v49, v90, v91 offset1:1
	ds_write2_b32 v49, v92, v93 offset0:2 offset1:3
	s_waitcnt vmcnt(27)
	v_add_u32_e32 v48, 0x1080, v36
	ds_write2_b32 v48, v94, v95 offset1:1
	ds_write2_b32 v48, v96, v97 offset0:2 offset1:3
	s_waitcnt vmcnt(26)
	v_add_u32_e32 v49, 0x14a0, v36
	ds_write2_b32 v49, v98, v99 offset1:1
	ds_write2_b32 v49, v100, v101 offset0:2 offset1:3
	s_waitcnt vmcnt(25)
	v_add_u32_e32 v48, 0x18c0, v36
	ds_write2_b32 v48, v102, v103 offset1:1
	ds_write2_b32 v48, v104, v105 offset0:2 offset1:3
	s_waitcnt vmcnt(24)
	v_add_u32_e32 v49, 0x1ce0, v36
	ds_write2_b32 v49, v106, v107 offset1:1
	ds_write2_b32 v49, v108, v109 offset0:2 offset1:3
	s_waitcnt vmcnt(23)
	v_add_u32_e32 v48, 0x2100, v36
	ds_write2_b32 v48, v110, v111 offset1:1
	ds_write2_b32 v48, v112, v113 offset0:2 offset1:3
	s_waitcnt vmcnt(22)
	v_add_u32_e32 v49, 0x2520, v36
	ds_write2_b32 v49, v114, v115 offset1:1
	ds_write2_b32 v49, v116, v117 offset0:2 offset1:3
	s_waitcnt vmcnt(21)
	v_add_u32_e32 v48, 0x2940, v36
	ds_write2_b32 v48, v118, v119 offset1:1
	ds_write2_b32 v48, v120, v121 offset0:2 offset1:3
	s_waitcnt vmcnt(20)
	v_add_u32_e32 v49, 0x2d60, v36
	ds_write2_b32 v49, v122, v123 offset1:1
	ds_write2_b32 v49, v124, v125 offset0:2 offset1:3
	s_waitcnt vmcnt(19)
	v_add_u32_e32 v48, 0x3180, v36
	ds_write2_b32 v48, v126, v127 offset1:1
	ds_write2_b32 v48, v128, v129 offset0:2 offset1:3
	s_waitcnt vmcnt(18)
	v_add_u32_e32 v49, 0x35a0, v36
	ds_write2_b32 v49, v130, v131 offset1:1
	ds_write2_b32 v49, v132, v133 offset0:2 offset1:3
	s_waitcnt vmcnt(17)
	v_add_u32_e32 v48, 0x39c0, v36
	ds_write2_b32 v48, v134, v135 offset1:1
	ds_write2_b32 v48, v136, v137 offset0:2 offset1:3
	s_waitcnt vmcnt(16)
	v_add_u32_e32 v49, 0x3de0, v36
	ds_write2_b32 v49, v138, v139 offset1:1
	ds_write2_b32 v49, v140, v141 offset0:2 offset1:3
	ds_read2_b32 v[244:245], v52 offset0:0 offset1:33
	ds_read2_b32 v[246:247], v52 offset0:66 offset1:99
	ds_read2_b32 v[248:249], v52 offset0:132 offset1:165
	ds_read2_b32 v[250:251], v52 offset0:198 offset1:231
	ds_read2_b32 v[38:39], v53 offset0:0 offset1:33
	ds_read2_b32 v[40:41], v53 offset0:66 offset1:99
	ds_read2_b32 v[42:43], v53 offset0:132 offset1:165
	ds_read2_b32 v[44:45], v53 offset0:198 offset1:231
	s_waitcnt lgkmcnt(4)
	v_cvt_pk_bf16_f32 v170, v244, v245
	v_cvt_pk_bf16_f32 v171, v246, v247
	v_cvt_pk_bf16_f32 v172, v248, v249
	v_cvt_pk_bf16_f32 v173, v250, v251
	global_store_dwordx4 v60, v[170:173], s[28:29] nt
	ds_read2_b32 v[244:245], v54 offset0:0 offset1:33
	ds_read2_b32 v[246:247], v54 offset0:66 offset1:99
	ds_read2_b32 v[248:249], v54 offset0:132 offset1:165
	ds_read2_b32 v[250:251], v54 offset0:198 offset1:231
	s_waitcnt lgkmcnt(4)
	v_cvt_pk_bf16_f32 v176, v38, v39
	v_cvt_pk_bf16_f32 v177, v40, v41
	v_cvt_pk_bf16_f32 v178, v42, v43
	v_cvt_pk_bf16_f32 v179, v44, v45
	global_store_dwordx4 v61, v[176:179], s[28:29] nt
	ds_read2_b32 v[38:39], v55 offset0:0 offset1:33
	ds_read2_b32 v[40:41], v55 offset0:66 offset1:99
	ds_read2_b32 v[42:43], v55 offset0:132 offset1:165
	ds_read2_b32 v[44:45], v55 offset0:198 offset1:231
	s_waitcnt lgkmcnt(4)
	v_cvt_pk_bf16_f32 v170, v244, v245
	v_cvt_pk_bf16_f32 v171, v246, v247
	v_cvt_pk_bf16_f32 v172, v248, v249
	v_cvt_pk_bf16_f32 v173, v250, v251
	global_store_dwordx4 v62, v[170:173], s[28:29] nt
	ds_read2_b32 v[244:245], v56 offset0:0 offset1:33
	ds_read2_b32 v[246:247], v56 offset0:66 offset1:99
	ds_read2_b32 v[248:249], v56 offset0:132 offset1:165
	ds_read2_b32 v[250:251], v56 offset0:198 offset1:231
	s_waitcnt lgkmcnt(4)
	v_cvt_pk_bf16_f32 v176, v38, v39
	v_cvt_pk_bf16_f32 v177, v40, v41
	v_cvt_pk_bf16_f32 v178, v42, v43
	v_cvt_pk_bf16_f32 v179, v44, v45
	global_store_dwordx4 v63, v[176:179], s[28:29] nt
	ds_read2_b32 v[38:39], v57 offset0:0 offset1:33
	ds_read2_b32 v[40:41], v57 offset0:66 offset1:99
	ds_read2_b32 v[42:43], v57 offset0:132 offset1:165
	ds_read2_b32 v[44:45], v57 offset0:198 offset1:231
	s_waitcnt lgkmcnt(4)
	v_cvt_pk_bf16_f32 v170, v244, v245
	v_cvt_pk_bf16_f32 v171, v246, v247
	v_cvt_pk_bf16_f32 v172, v248, v249
	v_cvt_pk_bf16_f32 v173, v250, v251
	global_store_dwordx4 v64, v[170:173], s[28:29] nt
	ds_read2_b32 v[244:245], v58 offset0:0 offset1:33
	ds_read2_b32 v[246:247], v58 offset0:66 offset1:99
	ds_read2_b32 v[248:249], v58 offset0:132 offset1:165
	ds_read2_b32 v[250:251], v58 offset0:198 offset1:231
	s_waitcnt lgkmcnt(4)
	v_cvt_pk_bf16_f32 v176, v38, v39
	v_cvt_pk_bf16_f32 v177, v40, v41
	v_cvt_pk_bf16_f32 v178, v42, v43
	v_cvt_pk_bf16_f32 v179, v44, v45
	global_store_dwordx4 v65, v[176:179], s[28:29] nt
	ds_read2_b32 v[38:39], v59 offset0:0 offset1:33
	ds_read2_b32 v[40:41], v59 offset0:66 offset1:99
	ds_read2_b32 v[42:43], v59 offset0:132 offset1:165
	ds_read2_b32 v[44:45], v59 offset0:198 offset1:231
	s_waitcnt lgkmcnt(4)
	v_cvt_pk_bf16_f32 v170, v244, v245
	v_cvt_pk_bf16_f32 v171, v246, v247
	v_cvt_pk_bf16_f32 v172, v248, v249
	v_cvt_pk_bf16_f32 v173, v250, v251
	global_store_dwordx4 v66, v[170:173], s[28:29] nt
	s_waitcnt lgkmcnt(0)
; __device__ __forceinline__ unsigned cvt_pk_bf16(float lo, float hi) { unsigned r; asm volatile("v_cvt_pk_bf16_f32 %0, %1, %2" : "=v"(r) : "v"(lo), "v"(hi)); return r; }
; #define GAS __attribute__((address_space(1)))
; #define LAS __attribute__((address_space(3)))
; #define LDS_WAIT() asm volatile("s_waitcnt lgkmcnt(0)" ::: "memory")
;     ...
;     for (int i = 0; i < 64; ++i) { const int kk = 2 * i + (lane >> 5); scr[kk * 33 + (lane & 31)] = W[(size_t)(k0 + kk) * N + n0 + (lane & 31)]; }
;     LDS_WAIT(); asm volatile("" ::: "memory");
;     const int c = lane & 15;
;     float gk[8];
;     if (gain) load8f(gain + k0 + 8 * c, gk); else {
; #pragma unroll
;         for (int e = 0; e < 8; ++e) gk[e] = 1.0f; }
; #pragma unroll
;     for (int j = 0; j < 8; ++j) { const int n = (lane >> 4) + 4 * j; const LAS float* s = scr + (8 * c) * 33 + n;
;         v4u o; o.x = cvt_pk_bf16(s[0 * 33] * gk[0], s[1 * 33] * gk[1]); o.y = cvt_pk_bf16(s[2 * 33] * gk[2], s[3 * 33] * gk[3]); o.z = cvt_pk_bf16(s[4 * 33] * gk[4], s[5 * 33] * gk[5]); o.w = cvt_pk_bf16(s[6 * 33] * gk[6], s[7 * 33] * gk[7]);
;         *(GAS v4u*)(WT + (size_t)(nd0 + n) * K + k0 + 8 * c) = o; }
	v_cvt_pk_bf16_f32 v176, v38, v39
	v_cvt_pk_bf16_f32 v177, v40, v41
	v_cvt_pk_bf16_f32 v178, v42, v43
	v_cvt_pk_bf16_f32 v179, v44, v45
	global_store_dwordx4 v67, v[176:179], s[28:29] nt
	s_add_i32 s16, s10, 0x800
	s_lshr_b32 s20, s16, 6
	s_and_b32 s24, s16, 63
	s_lshl_b32 s20, s20, 20
	s_lshl_b32 s24, s24, 7
	s_add_i32 s20, s20, s24
	s_add_i32 s20, s20, 0x9000000
	s_add_u32 s26, s0, s20
	s_addc_u32 s27, s1, 0
	global_load_dwordx4 v[78:81], v20, s[26:27] nt
	global_load_dwordx4 v[82:85], v21, s[26:27] nt
	global_load_dwordx4 v[86:89], v22, s[26:27] nt
	global_load_dwordx4 v[90:93], v23, s[26:27] nt
	global_load_dwordx4 v[94:97], v24, s[26:27] nt
	global_load_dwordx4 v[98:101], v25, s[26:27] nt
	global_load_dwordx4 v[102:105], v26, s[26:27] nt
	global_load_dwordx4 v[106:109], v27, s[26:27] nt
	global_load_dwordx4 v[110:113], v28, s[26:27] nt
	global_load_dwordx4 v[114:117], v29, s[26:27] nt
	global_load_dwordx4 v[118:121], v30, s[26:27] nt
	global_load_dwordx4 v[122:125], v31, s[26:27] nt
	global_load_dwordx4 v[126:129], v32, s[26:27] nt
	global_load_dwordx4 v[130:133], v33, s[26:27] nt
	global_load_dwordx4 v[134:137], v34, s[26:27] nt
	global_load_dwordx4 v[138:141], v35, s[26:27] nt
	s_add_i32 s16, s10, 0x400
	s_lshr_b32 s20, s16, 6
	s_and_b32 s24, s16, 63
	s_mul_i32 s24, s24, 0x60000
	s_lshl_b32 s20, s20, 8
	s_add_i32 s20, s20, s24
	s_add_i32 s20, s20, 0x4800000
	s_add_u32 s28, s2, s20
	s_addc_u32 s29, s3, 0
	s_waitcnt vmcnt(39)
	ds_write2_b32 v36, v142, v143 offset1:1
	ds_write2_b32 v36, v144, v145 offset0:2 offset1:3
	s_waitcnt vmcnt(38)
	v_add_u32_e32 v49, 0x420, v36
	ds_write2_b32 v49, v146, v147 offset1:1
	ds_write2_b32 v49, v148, v149 offset0:2 offset1:3
	s_waitcnt vmcnt(37)
	v_add_u32_e32 v48, 0x840, v36
	ds_write2_b32 v48, v150, v151 offset1:1
	ds_write2_b32 v48, v152, v153 offset0:2 offset1:3
	s_waitcnt vmcnt(36)
	v_add_u32_e32 v49, 0xc60, v36
	ds_write2_b32 v49, v154, v155 offset1:1
	ds_write2_b32 v49, v156, v157 offset0:2 offset1:3
	s_waitcnt vmcnt(35)
	v_add_u32_e32 v48, 0x1080, v36
	ds_write2_b32 v48, v158, v159 offset1:1
	ds_write2_b32 v48, v160, v161 offset0:2 offset1:3
	s_waitcnt vmcnt(34)
	v_add_u32_e32 v49, 0x14a0, v36
	ds_write2_b32 v49, v162, v163 offset1:1
	ds_write2_b32 v49, v164, v165 offset0:2 offset1:3
	s_waitcnt vmcnt(33)
	v_add_u32_e32 v48, 0x18c0, v36
	ds_write2_b32 v48, v196, v197 offset1:1
	ds_write2_b32 v48, v198, v199 offset0:2 offset1:3
	s_waitcnt vmcnt(32)
	v_add_u32_e32 v49, 0x1ce0, v36
	ds_write2_b32 v49, v200, v201 offset1:1
	ds_write2_b32 v49, v202, v203 offset0:2 offset1:3
	s_waitcnt vmcnt(31)
	v_add_u32_e32 v48, 0x2100, v36
	ds_write2_b32 v48, v204, v205 offset1:1
	ds_write2_b32 v48, v206, v207 offset0:2 offset1:3
	s_waitcnt vmcnt(30)
	v_add_u32_e32 v49, 0x2520, v36
	ds_write2_b32 v49, v208, v209 offset1:1
	ds_write2_b32 v49, v210, v211 offset0:2 offset1:3
	s_waitcnt vmcnt(29)
	v_add_u32_e32 v48, 0x2940, v36
	ds_write2_b32 v48, v212, v213 offset1:1
	ds_write2_b32 v48, v214, v215 offset0:2 offset1:3
	s_waitcnt vmcnt(28)
	v_add_u32_e32 v49, 0x2d60, v36
	ds_write2_b32 v49, v216, v217 offset1:1
	ds_write2_b32 v49, v218, v219 offset0:2 offset1:3
	s_waitcnt vmcnt(27)
	v_add_u32_e32 v48, 0x3180, v36
	ds_write2_b32 v48, v228, v229 offset1:1
	ds_write2_b32 v48, v230, v231 offset0:2 offset1:3
	s_waitcnt vmcnt(26)
	v_add_u32_e32 v49, 0x35a0, v36
	ds_write2_b32 v49, v232, v233 offset1:1
	ds_write2_b32 v49, v234, v235 offset0:2 offset1:3
	s_waitcnt vmcnt(25)
	v_add_u32_e32 v48, 0x39c0, v36
	ds_write2_b32 v48, v236, v237 offset1:1
	ds_write2_b32 v48, v238, v239 offset0:2 offset1:3
	s_waitcnt vmcnt(24)
	v_add_u32_e32 v49, 0x3de0, v36
	ds_write2_b32 v49, v240, v241 offset1:1
	ds_write2_b32 v49, v242, v243 offset0:2 offset1:3
	ds_read2_b32 v[244:245], v52 offset0:0 offset1:33
	ds_read2_b32 v[246:247], v52 offset0:66 offset1:99
	ds_read2_b32 v[248:249], v52 offset0:132 offset1:165
	ds_read2_b32 v[250:251], v52 offset0:198 offset1:231
	ds_read2_b32 v[38:39], v53 offset0:0 offset1:33
	ds_read2_b32 v[40:41], v53 offset0:66 offset1:99
	ds_read2_b32 v[42:43], v53 offset0:132 offset1:165
	ds_read2_b32 v[44:45], v53 offset0:198 offset1:231
	s_waitcnt lgkmcnt(4)
	v_cvt_pk_bf16_f32 v170, v244, v245
	v_cvt_pk_bf16_f32 v171, v246, v247
	v_cvt_pk_bf16_f32 v172, v248, v249
	v_cvt_pk_bf16_f32 v173, v250, v251
	global_store_dwordx4 v60, v[170:173], s[28:29] nt
	ds_read2_b32 v[244:245], v54 offset0:0 offset1:33
	ds_read2_b32 v[246:247], v54 offset0:66 offset1:99
	ds_read2_b32 v[248:249], v54 offset0:132 offset1:165
	ds_read2_b32 v[250:251], v54 offset0:198 offset1:231
	s_waitcnt lgkmcnt(4)
	v_cvt_pk_bf16_f32 v176, v38, v39
	v_cvt_pk_bf16_f32 v177, v40, v41
	v_cvt_pk_bf16_f32 v178, v42, v43
	v_cvt_pk_bf16_f32 v179, v44, v45
	global_store_dwordx4 v61, v[176:179], s[28:29] nt
	ds_read2_b32 v[38:39], v55 offset0:0 offset1:33
	ds_read2_b32 v[40:41], v55 offset0:66 offset1:99
	ds_read2_b32 v[42:43], v55 offset0:132 offset1:165
	ds_read2_b32 v[44:45], v55 offset0:198 offset1:231
	s_waitcnt lgkmcnt(4)
	v_cvt_pk_bf16_f32 v170, v244, v245
	v_cvt_pk_bf16_f32 v171, v246, v247
	v_cvt_pk_bf16_f32 v172, v248, v249
	v_cvt_pk_bf16_f32 v173, v250, v251
	global_store_dwordx4 v62, v[170:173], s[28:29] nt
	ds_read2_b32 v[244:245], v56 offset0:0 offset1:33
	ds_read2_b32 v[246:247], v56 offset0:66 offset1:99
	ds_read2_b32 v[248:249], v56 offset0:132 offset1:165
	ds_read2_b32 v[250:251], v56 offset0:198 offset1:231
	s_waitcnt lgkmcnt(4)
	v_cvt_pk_bf16_f32 v176, v38, v39
	v_cvt_pk_bf16_f32 v177, v40, v41
	v_cvt_pk_bf16_f32 v178, v42, v43
	v_cvt_pk_bf16_f32 v179, v44, v45
	global_store_dwordx4 v63, v[176:179], s[28:29] nt
	ds_read2_b32 v[38:39], v57 offset0:0 offset1:33
	ds_read2_b32 v[40:41], v57 offset0:66 offset1:99
	ds_read2_b32 v[42:43], v57 offset0:132 offset1:165
	ds_read2_b32 v[44:45], v57 offset0:198 offset1:231
	s_waitcnt lgkmcnt(4)
; __device__ __forceinline__ unsigned cvt_pk_bf16(float lo, float hi) { unsigned r; asm volatile("v_cvt_pk_bf16_f32 %0, %1, %2" : "=v"(r) : "v"(lo), "v"(hi)); return r; }
; #define GAS __attribute__((address_space(1)))
; #define LAS __attribute__((address_space(3)))
; #define LDS_WAIT() asm volatile("s_waitcnt lgkmcnt(0)" ::: "memory")
;     ...
;     for (int i = 0; i < 64; ++i) { const int kk = 2 * i + (lane >> 5); scr[kk * 33 + (lane & 31)] = W[(size_t)(k0 + kk) * N + n0 + (lane & 31)]; }
;     LDS_WAIT(); asm volatile("" ::: "memory");
;     const int c = lane & 15;
;     float gk[8];
;     if (gain) load8f(gain + k0 + 8 * c, gk); else {
; #pragma unroll
;         for (int e = 0; e < 8; ++e) gk[e] = 1.0f; }
; #pragma unroll
;     for (int j = 0; j < 8; ++j) { const int n = (lane >> 4) + 4 * j; const LAS float* s = scr + (8 * c) * 33 + n;
;         v4u o; o.x = cvt_pk_bf16(s[0 * 33] * gk[0], s[1 * 33] * gk[1]); o.y = cvt_pk_bf16(s[2 * 33] * gk[2], s[3 * 33] * gk[3]); o.z = cvt_pk_bf16(s[4 * 33] * gk[4], s[5 * 33] * gk[5]); o.w = cvt_pk_bf16(s[6 * 33] * gk[6], s[7 * 33] * gk[7]);
;         *(GAS v4u*)(WT + (size_t)(nd0 + n) * K + k0 + 8 * c) = o; }
	v_cvt_pk_bf16_f32 v170, v244, v245
	v_cvt_pk_bf16_f32 v171, v246, v247
	v_cvt_pk_bf16_f32 v172, v248, v249
	v_cvt_pk_bf16_f32 v173, v250, v251
	global_store_dwordx4 v64, v[170:173], s[28:29] nt
	ds_read2_b32 v[244:245], v58 offset0:0 offset1:33
	ds_read2_b32 v[246:247], v58 offset0:66 offset1:99
	ds_read2_b32 v[248:249], v58 offset0:132 offset1:165
	ds_read2_b32 v[250:251], v58 offset0:198 offset1:231
	s_waitcnt lgkmcnt(4)
	v_cvt_pk_bf16_f32 v176, v38, v39
	v_cvt_pk_bf16_f32 v177, v40, v41
	v_cvt_pk_bf16_f32 v178, v42, v43
	v_cvt_pk_bf16_f32 v179, v44, v45
	global_store_dwordx4 v65, v[176:179], s[28:29] nt
	ds_read2_b32 v[38:39], v59 offset0:0 offset1:33
	ds_read2_b32 v[40:41], v59 offset0:66 offset1:99
	ds_read2_b32 v[42:43], v59 offset0:132 offset1:165
	ds_read2_b32 v[44:45], v59 offset0:198 offset1:231
	s_waitcnt lgkmcnt(4)
	v_cvt_pk_bf16_f32 v170, v244, v245
	v_cvt_pk_bf16_f32 v171, v246, v247
	v_cvt_pk_bf16_f32 v172, v248, v249
	v_cvt_pk_bf16_f32 v173, v250, v251
	global_store_dwordx4 v66, v[170:173], s[28:29] nt
	s_waitcnt lgkmcnt(0)
	v_cvt_pk_bf16_f32 v176, v38, v39
	v_cvt_pk_bf16_f32 v177, v40, v41
	v_cvt_pk_bf16_f32 v178, v42, v43
	v_cvt_pk_bf16_f32 v179, v44, v45
	global_store_dwordx4 v67, v[176:179], s[28:29] nt
	s_add_i32 s16, s10, 0x800
	s_lshr_b32 s20, s16, 6
	s_and_b32 s24, s16, 63
	s_mul_i32 s24, s24, 0x60000
	s_lshl_b32 s20, s20, 8
	s_add_i32 s20, s20, s24
	s_add_i32 s20, s20, 0x4800000
	s_add_u32 s28, s2, s20
	s_addc_u32 s29, s3, 0
	s_waitcnt vmcnt(23)
	ds_write2_b32 v36, v78, v79 offset1:1
	ds_write2_b32 v36, v80, v81 offset0:2 offset1:3
	s_waitcnt vmcnt(22)
	v_add_u32_e32 v49, 0x420, v36
	ds_write2_b32 v49, v82, v83 offset1:1
	ds_write2_b32 v49, v84, v85 offset0:2 offset1:3
	s_waitcnt vmcnt(21)
	v_add_u32_e32 v48, 0x840, v36
	ds_write2_b32 v48, v86, v87 offset1:1
	ds_write2_b32 v48, v88, v89 offset0:2 offset1:3
	s_waitcnt vmcnt(20)
	v_add_u32_e32 v49, 0xc60, v36
	ds_write2_b32 v49, v90, v91 offset1:1
	ds_write2_b32 v49, v92, v93 offset0:2 offset1:3
	s_waitcnt vmcnt(19)
	v_add_u32_e32 v48, 0x1080, v36
	ds_write2_b32 v48, v94, v95 offset1:1
	ds_write2_b32 v48, v96, v97 offset0:2 offset1:3
	s_waitcnt vmcnt(18)
	v_add_u32_e32 v49, 0x14a0, v36
	ds_write2_b32 v49, v98, v99 offset1:1
	ds_write2_b32 v49, v100, v101 offset0:2 offset1:3
	s_waitcnt vmcnt(17)
	v_add_u32_e32 v48, 0x18c0, v36
	ds_write2_b32 v48, v102, v103 offset1:1
	ds_write2_b32 v48, v104, v105 offset0:2 offset1:3
	s_waitcnt vmcnt(16)
	v_add_u32_e32 v49, 0x1ce0, v36
	ds_write2_b32 v49, v106, v107 offset1:1
	ds_write2_b32 v49, v108, v109 offset0:2 offset1:3
	s_waitcnt vmcnt(15)
	v_add_u32_e32 v48, 0x2100, v36
	ds_write2_b32 v48, v110, v111 offset1:1
	ds_write2_b32 v48, v112, v113 offset0:2 offset1:3
	s_waitcnt vmcnt(14)
	v_add_u32_e32 v49, 0x2520, v36
	ds_write2_b32 v49, v114, v115 offset1:1
	ds_write2_b32 v49, v116, v117 offset0:2 offset1:3
	s_waitcnt vmcnt(13)
	v_add_u32_e32 v48, 0x2940, v36
	ds_write2_b32 v48, v118, v119 offset1:1
	ds_write2_b32 v48, v120, v121 offset0:2 offset1:3
	s_waitcnt vmcnt(12)
	v_add_u32_e32 v49, 0x2d60, v36
	ds_write2_b32 v49, v122, v123 offset1:1
	ds_write2_b32 v49, v124, v125 offset0:2 offset1:3
	s_waitcnt vmcnt(11)
	v_add_u32_e32 v48, 0x3180, v36
	ds_write2_b32 v48, v126, v127 offset1:1
	ds_write2_b32 v48, v128, v129 offset0:2 offset1:3
	s_waitcnt vmcnt(10)
	v_add_u32_e32 v49, 0x35a0, v36
	ds_write2_b32 v49, v130, v131 offset1:1
	ds_write2_b32 v49, v132, v133 offset0:2 offset1:3
	s_waitcnt vmcnt(9)
	v_add_u32_e32 v48, 0x39c0, v36
	ds_write2_b32 v48, v134, v135 offset1:1
	ds_write2_b32 v48, v136, v137 offset0:2 offset1:3
	s_waitcnt vmcnt(8)
; __device__ __forceinline__ unsigned cvt_pk_bf16(float lo, float hi) { unsigned r; asm volatile("v_cvt_pk_bf16_f32 %0, %1, %2" : "=v"(r) : "v"(lo), "v"(hi)); return r; }
; #define GAS __attribute__((address_space(1)))
; #define LAS __attribute__((address_space(3)))
; #define LDS_WAIT() asm volatile("s_waitcnt lgkmcnt(0)" ::: "memory")
;     ...
;     for (int i = 0; i < 64; ++i) { const int kk = 2 * i + (lane >> 5); scr[kk * 33 + (lane & 31)] = W[(size_t)(k0 + kk) * N + n0 + (lane & 31)]; }
;     LDS_WAIT(); asm volatile("" ::: "memory");
;     const int c = lane & 15;
;     float gk[8];
;     if (gain) load8f(gain + k0 + 8 * c, gk); else {
; #pragma unroll
;         for (int e = 0; e < 8; ++e) gk[e] = 1.0f; }
; #pragma unroll
;     for (int j = 0; j < 8; ++j) { const int n = (lane >> 4) + 4 * j; const LAS float* s = scr + (8 * c) * 33 + n;
;         v4u o; o.x = cvt_pk_bf16(s[0 * 33] * gk[0], s[1 * 33] * gk[1]); o.y = cvt_pk_bf16(s[2 * 33] * gk[2], s[3 * 33] * gk[3]); o.z = cvt_pk_bf16(s[4 * 33] * gk[4], s[5 * 33] * gk[5]); o.w = cvt_pk_bf16(s[6 * 33] * gk[6], s[7 * 33] * gk[7]);
;         *(GAS v4u*)(WT + (size_t)(nd0 + n) * K + k0 + 8 * c) = o; }
	v_add_u32_e32 v49, 0x3de0, v36
	ds_write2_b32 v49, v138, v139 offset1:1
	ds_write2_b32 v49, v140, v141 offset0:2 offset1:3
	ds_read2_b32 v[244:245], v52 offset0:0 offset1:33
	ds_read2_b32 v[246:247], v52 offset0:66 offset1:99
	ds_read2_b32 v[248:249], v52 offset0:132 offset1:165
	ds_read2_b32 v[250:251], v52 offset0:198 offset1:231
	ds_read2_b32 v[38:39], v53 offset0:0 offset1:33
	ds_read2_b32 v[40:41], v53 offset0:66 offset1:99
	ds_read2_b32 v[42:43], v53 offset0:132 offset1:165
	ds_read2_b32 v[44:45], v53 offset0:198 offset1:231
	s_waitcnt lgkmcnt(4)
	v_cvt_pk_bf16_f32 v170, v244, v245
	v_cvt_pk_bf16_f32 v171, v246, v247
	v_cvt_pk_bf16_f32 v172, v248, v249
	v_cvt_pk_bf16_f32 v173, v250, v251
	global_store_dwordx4 v60, v[170:173], s[28:29] nt
	ds_read2_b32 v[244:245], v54 offset0:0 offset1:33
	ds_read2_b32 v[246:247], v54 offset0:66 offset1:99
	ds_read2_b32 v[248:249], v54 offset0:132 offset1:165
	ds_read2_b32 v[250:251], v54 offset0:198 offset1:231
	s_waitcnt lgkmcnt(4)
	v_cvt_pk_bf16_f32 v176, v38, v39
	v_cvt_pk_bf16_f32 v177, v40, v41
	v_cvt_pk_bf16_f32 v178, v42, v43
	v_cvt_pk_bf16_f32 v179, v44, v45
	global_store_dwordx4 v61, v[176:179], s[28:29] nt
	ds_read2_b32 v[38:39], v55 offset0:0 offset1:33
	ds_read2_b32 v[40:41], v55 offset0:66 offset1:99
	ds_read2_b32 v[42:43], v55 offset0:132 offset1:165
	ds_read2_b32 v[44:45], v55 offset0:198 offset1:231
	s_waitcnt lgkmcnt(4)
	v_cvt_pk_bf16_f32 v170, v244, v245
	v_cvt_pk_bf16_f32 v171, v246, v247
	v_cvt_pk_bf16_f32 v172, v248, v249
	v_cvt_pk_bf16_f32 v173, v250, v251
	global_store_dwordx4 v62, v[170:173], s[28:29] nt
	ds_read2_b32 v[244:245], v56 offset0:0 offset1:33
	ds_read2_b32 v[246:247], v56 offset0:66 offset1:99
	ds_read2_b32 v[248:249], v56 offset0:132 offset1:165
	ds_read2_b32 v[250:251], v56 offset0:198 offset1:231
	s_waitcnt lgkmcnt(4)
	v_cvt_pk_bf16_f32 v176, v38, v39
	v_cvt_pk_bf16_f32 v177, v40, v41
	v_cvt_pk_bf16_f32 v178, v42, v43
	v_cvt_pk_bf16_f32 v179, v44, v45
	global_store_dwordx4 v63, v[176:179], s[28:29] nt
	ds_read2_b32 v[38:39], v57 offset0:0 offset1:33
	ds_read2_b32 v[40:41], v57 offset0:66 offset1:99
	ds_read2_b32 v[42:43], v57 offset0:132 offset1:165
	ds_read2_b32 v[44:45], v57 offset0:198 offset1:231
	s_waitcnt lgkmcnt(4)
	v_cvt_pk_bf16_f32 v170, v244, v245
	v_cvt_pk_bf16_f32 v171, v246, v247
	v_cvt_pk_bf16_f32 v172, v248, v249
	v_cvt_pk_bf16_f32 v173, v250, v251
	global_store_dwordx4 v64, v[170:173], s[28:29] nt
	ds_read2_b32 v[244:245], v58 offset0:0 offset1:33
	ds_read2_b32 v[246:247], v58 offset0:66 offset1:99
	ds_read2_b32 v[248:249], v58 offset0:132 offset1:165
	ds_read2_b32 v[250:251], v58 offset0:198 offset1:231
	s_waitcnt lgkmcnt(4)
	v_cvt_pk_bf16_f32 v176, v38, v39
	v_cvt_pk_bf16_f32 v177, v40, v41
	v_cvt_pk_bf16_f32 v178, v42, v43
	v_cvt_pk_bf16_f32 v179, v44, v45
	global_store_dwordx4 v65, v[176:179], s[28:29] nt
	ds_read2_b32 v[38:39], v59 offset0:0 offset1:33
	ds_read2_b32 v[40:41], v59 offset0:66 offset1:99
	ds_read2_b32 v[42:43], v59 offset0:132 offset1:165
	ds_read2_b32 v[44:45], v59 offset0:198 offset1:231
	s_waitcnt lgkmcnt(4)
	v_cvt_pk_bf16_f32 v170, v244, v245
	v_cvt_pk_bf16_f32 v171, v246, v247
	v_cvt_pk_bf16_f32 v172, v248, v249
	v_cvt_pk_bf16_f32 v173, v250, v251
	global_store_dwordx4 v66, v[170:173], s[28:29] nt
	s_waitcnt lgkmcnt(0)
	v_cvt_pk_bf16_f32 v176, v38, v39
	v_cvt_pk_bf16_f32 v177, v40, v41
	v_cvt_pk_bf16_f32 v178, v42, v43
	v_cvt_pk_bf16_f32 v179, v44, v45
	global_store_dwordx4 v67, v[176:179], s[28:29] nt
